# S5 pass 2 items: the 16 bu rows of a sub-step are read from LDS up front, recurrence runs from registers
# baseline (speedup 1.0000x reference)
; DI u16 f2bf(float x) { return (u16)(pk2(x, 0.f) & 0xffffu); }
; template <bool OUT>
; DI void s5_item(int wv0, PP p, int item, unsigned char* smem) {
;     ...
;     for (int t = 0; t < 16; ++t) {
;       const float bur = sBU[t * 132 + lane], bui = sBU[t * 132 + 64 + lane];
;       const float nr = lbr * hr - lbi * hi + bur;
;       const float nim = lbr * hi + lbi * hr + bui;
;       hr = nr;
;       hi = nim;
;       if (OUT) {
;         sH[t * 136 + lane] = f2bf(hr);
;         sH[t * 136 + 64 + lane] = f2bf(hi);
;       }
;     }
.LBB0_784:
	v_add_u32_e32 v117, 32, v62
	v_add_u32_e32 v118, 1088, v62
	v_add_u32_e32 v119, 2144, v62
	v_add_u32_e32 v120, 3200, v62
	v_add_u32_e32 v121, 4256, v62
	v_add_u32_e32 v122, 5312, v62
	v_add_u32_e32 v123, 6368, v62
	v_add_u32_e32 v124, 7424, v62
	ds_read2st64_b32 v[152:153], v117 offset1:1
	ds_read2_b32 v[154:155], v117 offset0:132 offset1:196
	ds_read2st64_b32 v[156:157], v118 offset1:1
	ds_read2_b32 v[158:159], v118 offset0:132 offset1:196
	ds_read2st64_b32 v[160:161], v119 offset1:1
	ds_read2_b32 v[162:163], v119 offset0:132 offset1:196
	ds_read2st64_b32 v[164:165], v120 offset1:1
	ds_read2_b32 v[166:167], v120 offset0:132 offset1:196
	ds_read2st64_b32 v[168:169], v121 offset1:1
	ds_read2_b32 v[170:171], v121 offset0:132 offset1:196
	ds_read2st64_b32 v[172:173], v122 offset1:1
	ds_read2_b32 v[174:175], v122 offset0:132 offset1:196
	ds_read2st64_b32 v[176:177], v123 offset1:1
	ds_read2_b32 v[178:179], v123 offset0:132 offset1:196
	ds_read2st64_b32 v[180:181], v124 offset1:1
	ds_read2_b32 v[182:183], v124 offset0:132 offset1:196
	v_add_u32_e32 v126, 0x12820, v63
	s_waitcnt lgkmcnt(0)
	v_pk_mul_f32 v[184:185], v[70:71], v[68:69] op_sel:[0,1]
	v_pk_fma_f32 v[186:187], v[66:67], v[68:69], v[184:185] neg_lo:[0,0,1] neg_hi:[0,0,1]
	v_pk_fma_f32 v[188:189], v[66:67], v[68:69], v[184:185] op_sel_hi:[1,0,1]
	v_mov_b32_e32 v187, v189
	v_pk_add_f32 v[192:193], v[186:187], v[152:153]
	v_cvt_pk_bf16_f32 v190, v192, s0
	ds_write_b16 v126, v190
	v_cvt_pk_bf16_f32 v191, v193, s0
	ds_write_b16 v126, v191 offset:128
	v_pk_mul_f32 v[184:185], v[70:71], v[192:193] op_sel:[0,1]
	v_pk_fma_f32 v[186:187], v[66:67], v[192:193], v[184:185] neg_lo:[0,0,1] neg_hi:[0,0,1]
	v_pk_fma_f32 v[188:189], v[66:67], v[192:193], v[184:185] op_sel_hi:[1,0,1]
	v_mov_b32_e32 v187, v189
	v_pk_add_f32 v[68:69], v[186:187], v[154:155]
	v_cvt_pk_bf16_f32 v190, v68, s0
	ds_write_b16 v126, v190 offset:272
	v_cvt_pk_bf16_f32 v191, v69, s0
	ds_write_b16 v126, v191 offset:400
	v_pk_mul_f32 v[184:185], v[70:71], v[68:69] op_sel:[0,1]
	v_pk_fma_f32 v[186:187], v[66:67], v[68:69], v[184:185] neg_lo:[0,0,1] neg_hi:[0,0,1]
	v_pk_fma_f32 v[188:189], v[66:67], v[68:69], v[184:185] op_sel_hi:[1,0,1]
	v_mov_b32_e32 v187, v189
	v_pk_add_f32 v[192:193], v[186:187], v[156:157]
	v_cvt_pk_bf16_f32 v190, v192, s0
	ds_write_b16 v126, v190 offset:544
	v_cvt_pk_bf16_f32 v191, v193, s0
	ds_write_b16 v126, v191 offset:672
	v_pk_mul_f32 v[184:185], v[70:71], v[192:193] op_sel:[0,1]
	v_pk_fma_f32 v[186:187], v[66:67], v[192:193], v[184:185] neg_lo:[0,0,1] neg_hi:[0,0,1]
	v_pk_fma_f32 v[188:189], v[66:67], v[192:193], v[184:185] op_sel_hi:[1,0,1]
	v_mov_b32_e32 v187, v189
	v_pk_add_f32 v[68:69], v[186:187], v[158:159]
	v_cvt_pk_bf16_f32 v190, v68, s0
	ds_write_b16 v126, v190 offset:816
	v_cvt_pk_bf16_f32 v191, v69, s0
	ds_write_b16 v126, v191 offset:944
	v_pk_mul_f32 v[184:185], v[70:71], v[68:69] op_sel:[0,1]
	v_pk_fma_f32 v[186:187], v[66:67], v[68:69], v[184:185] neg_lo:[0,0,1] neg_hi:[0,0,1]
	v_pk_fma_f32 v[188:189], v[66:67], v[68:69], v[184:185] op_sel_hi:[1,0,1]
	v_mov_b32_e32 v187, v189
	v_pk_add_f32 v[192:193], v[186:187], v[160:161]
	v_cvt_pk_bf16_f32 v190, v192, s0
	ds_write_b16 v126, v190 offset:1088
	v_cvt_pk_bf16_f32 v191, v193, s0
	ds_write_b16 v126, v191 offset:1216
	v_pk_mul_f32 v[184:185], v[70:71], v[192:193] op_sel:[0,1]
	v_pk_fma_f32 v[186:187], v[66:67], v[192:193], v[184:185] neg_lo:[0,0,1] neg_hi:[0,0,1]
	v_pk_fma_f32 v[188:189], v[66:67], v[192:193], v[184:185] op_sel_hi:[1,0,1]
	v_mov_b32_e32 v187, v189
	v_pk_add_f32 v[68:69], v[186:187], v[162:163]
	v_cvt_pk_bf16_f32 v190, v68, s0
	ds_write_b16 v126, v190 offset:1360
	v_cvt_pk_bf16_f32 v191, v69, s0
	ds_write_b16 v126, v191 offset:1488
	v_pk_mul_f32 v[184:185], v[70:71], v[68:69] op_sel:[0,1]
	v_pk_fma_f32 v[186:187], v[66:67], v[68:69], v[184:185] neg_lo:[0,0,1] neg_hi:[0,0,1]
	v_pk_fma_f32 v[188:189], v[66:67], v[68:69], v[184:185] op_sel_hi:[1,0,1]
	v_mov_b32_e32 v187, v189
	v_pk_add_f32 v[192:193], v[186:187], v[164:165]
	v_cvt_pk_bf16_f32 v190, v192, s0
	ds_write_b16 v126, v190 offset:1632
	v_cvt_pk_bf16_f32 v191, v193, s0
	ds_write_b16 v126, v191 offset:1760
	v_pk_mul_f32 v[184:185], v[70:71], v[192:193] op_sel:[0,1]
	v_pk_fma_f32 v[186:187], v[66:67], v[192:193], v[184:185] neg_lo:[0,0,1] neg_hi:[0,0,1]
	v_pk_fma_f32 v[188:189], v[66:67], v[192:193], v[184:185] op_sel_hi:[1,0,1]
	v_mov_b32_e32 v187, v189
	v_pk_add_f32 v[68:69], v[186:187], v[166:167]
	v_cvt_pk_bf16_f32 v190, v68, s0
	ds_write_b16 v126, v190 offset:1904
	v_cvt_pk_bf16_f32 v191, v69, s0
	ds_write_b16 v126, v191 offset:2032
	v_pk_mul_f32 v[184:185], v[70:71], v[68:69] op_sel:[0,1]
	v_pk_fma_f32 v[186:187], v[66:67], v[68:69], v[184:185] neg_lo:[0,0,1] neg_hi:[0,0,1]
	v_pk_fma_f32 v[188:189], v[66:67], v[68:69], v[184:185] op_sel_hi:[1,0,1]
	v_mov_b32_e32 v187, v189
	v_pk_add_f32 v[192:193], v[186:187], v[168:169]
	v_cvt_pk_bf16_f32 v190, v192, s0
	ds_write_b16 v126, v190 offset:2176
	v_cvt_pk_bf16_f32 v191, v193, s0
	ds_write_b16 v126, v191 offset:2304
	v_pk_mul_f32 v[184:185], v[70:71], v[192:193] op_sel:[0,1]
	v_pk_fma_f32 v[186:187], v[66:67], v[192:193], v[184:185] neg_lo:[0,0,1] neg_hi:[0,0,1]
	v_pk_fma_f32 v[188:189], v[66:67], v[192:193], v[184:185] op_sel_hi:[1,0,1]
	v_mov_b32_e32 v187, v189
	v_pk_add_f32 v[68:69], v[186:187], v[170:171]
	v_cvt_pk_bf16_f32 v190, v68, s0
	ds_write_b16 v126, v190 offset:2448
	v_cvt_pk_bf16_f32 v191, v69, s0
	ds_write_b16 v126, v191 offset:2576
	v_pk_mul_f32 v[184:185], v[70:71], v[68:69] op_sel:[0,1]
	v_pk_fma_f32 v[186:187], v[66:67], v[68:69], v[184:185] neg_lo:[0,0,1] neg_hi:[0,0,1]
; DI u16 f2bf(float x) { return (u16)(pk2(x, 0.f) & 0xffffu); }
; DI float bf2f(u16 h) { return __uint_as_float(((unsigned)h) << 16); }
; DI f32x4 mfma16(bf16x8 a, bf16x8 b, f32x4 c) { return __builtin_amdgcn_mfma_f32_16x16x32_bf16(a, b, c, 0, 0, 0); }
; DI float gelu_t(float x) {
;   float u = 0.7978845608f * (x + 0.044715f * x * x * x);
;   float e = __expf(2.f * u);
;   float th = 1.f - 2.f / (e + 1.f);
;   return 0.5f * x * (1.f + th);
; }
; template <bool OUT>
; DI void s5_item(int wv0, PP p, int item, unsigned char* smem) {
;     ...
;     for (int t = 0; t < 16; ++t) {
;       const float bur = sBU[t * 132 + lane], bui = sBU[t * 132 + 64 + lane];
;       const float nr = lbr * hr - lbi * hi + bur;
;       const float nim = lbr * hi + lbi * hr + bui;
;       hr = nr;
;       hi = nim;
;       if (OUT) {
;         sH[t * 136 + lane] = f2bf(hr);
;         sH[t * 136 + 64 + lane] = f2bf(hi);
;       }
;     }
;     __syncthreads();
;     if (OUT) {
;       f32x4 y = {0.f, 0.f, 0.f, 0.f};
; #pragma unroll
;       for (int ks = 0; ks < 4; ++ks) y = mfma16(*(const bf16x8*)(sH + fr * 136 + 32 * ks + 8 * fq), cf[ks], y);
; #pragma unroll
;       for (int j = 0; j < 4; ++j) {
;         const size_t o = (size_t)(sub * 16 + 4 * fq + j) * 512 + fr;
;         YS[o] = f2bf(gelu_t(y[j] + dk * bf2f(usk[sub][j])));
	v_pk_fma_f32 v[188:189], v[66:67], v[68:69], v[184:185] op_sel_hi:[1,0,1]
	v_mov_b32_e32 v187, v189
	v_pk_add_f32 v[192:193], v[186:187], v[172:173]
	v_cvt_pk_bf16_f32 v190, v192, s0
	ds_write_b16 v126, v190 offset:2720
	v_cvt_pk_bf16_f32 v191, v193, s0
	ds_write_b16 v126, v191 offset:2848
	v_pk_mul_f32 v[184:185], v[70:71], v[192:193] op_sel:[0,1]
	v_pk_fma_f32 v[186:187], v[66:67], v[192:193], v[184:185] neg_lo:[0,0,1] neg_hi:[0,0,1]
	v_pk_fma_f32 v[188:189], v[66:67], v[192:193], v[184:185] op_sel_hi:[1,0,1]
	v_mov_b32_e32 v187, v189
	v_pk_add_f32 v[68:69], v[186:187], v[174:175]
	v_cvt_pk_bf16_f32 v190, v68, s0
	ds_write_b16 v126, v190 offset:2992
	v_cvt_pk_bf16_f32 v191, v69, s0
	ds_write_b16 v126, v191 offset:3120
	v_pk_mul_f32 v[184:185], v[70:71], v[68:69] op_sel:[0,1]
	v_pk_fma_f32 v[186:187], v[66:67], v[68:69], v[184:185] neg_lo:[0,0,1] neg_hi:[0,0,1]
	v_pk_fma_f32 v[188:189], v[66:67], v[68:69], v[184:185] op_sel_hi:[1,0,1]
	v_mov_b32_e32 v187, v189
	v_pk_add_f32 v[192:193], v[186:187], v[176:177]
	v_cvt_pk_bf16_f32 v190, v192, s0
	ds_write_b16 v126, v190 offset:3264
	v_cvt_pk_bf16_f32 v191, v193, s0
	ds_write_b16 v126, v191 offset:3392
	v_pk_mul_f32 v[184:185], v[70:71], v[192:193] op_sel:[0,1]
	v_pk_fma_f32 v[186:187], v[66:67], v[192:193], v[184:185] neg_lo:[0,0,1] neg_hi:[0,0,1]
	v_pk_fma_f32 v[188:189], v[66:67], v[192:193], v[184:185] op_sel_hi:[1,0,1]
	v_mov_b32_e32 v187, v189
	v_pk_add_f32 v[68:69], v[186:187], v[178:179]
	v_cvt_pk_bf16_f32 v190, v68, s0
	ds_write_b16 v126, v190 offset:3536
	v_cvt_pk_bf16_f32 v191, v69, s0
	ds_write_b16 v126, v191 offset:3664
	v_pk_mul_f32 v[184:185], v[70:71], v[68:69] op_sel:[0,1]
	v_pk_fma_f32 v[186:187], v[66:67], v[68:69], v[184:185] neg_lo:[0,0,1] neg_hi:[0,0,1]
	v_pk_fma_f32 v[188:189], v[66:67], v[68:69], v[184:185] op_sel_hi:[1,0,1]
	v_mov_b32_e32 v187, v189
	v_pk_add_f32 v[192:193], v[186:187], v[180:181]
	v_cvt_pk_bf16_f32 v190, v192, s0
	ds_write_b16 v126, v190 offset:3808
	v_cvt_pk_bf16_f32 v191, v193, s0
	ds_write_b16 v126, v191 offset:3936
	v_pk_mul_f32 v[184:185], v[70:71], v[192:193] op_sel:[0,1]
	v_pk_fma_f32 v[186:187], v[66:67], v[192:193], v[184:185] neg_lo:[0,0,1] neg_hi:[0,0,1]
	v_pk_fma_f32 v[188:189], v[66:67], v[192:193], v[184:185] op_sel_hi:[1,0,1]
	v_mov_b32_e32 v187, v189
	v_pk_add_f32 v[68:69], v[186:187], v[182:183]
	v_cvt_pk_bf16_f32 v190, v68, s0
	ds_write_b16 v126, v190 offset:4080
	v_cvt_pk_bf16_f32 v191, v69, s0
	ds_write_b16 v126, v191 offset:4208
	s_lshl_b64 s[2:3], s[2:3], 1
	v_readlane_b32 s4, v247, 42
	s_add_u32 s2, s4, s2
	v_readlane_b32 s4, v247, 43
	s_addc_u32 s3, s4, s3
	v_readlane_b32 s4, v247, 46
	s_waitcnt lgkmcnt(0)
	s_barrier
	v_add_u32_e32 v62, s4, v110
	v_add_u32_e32 v0, v62, v0
	ds_read_b128 v[62:65], v0
	ds_read_b128 v[110:113], v0 offset:64
	s_waitcnt vmcnt(15)
	v_lshlrev_b32_e32 v109, 16, v109
	s_waitcnt lgkmcnt(1)
	v_mfma_f32_16x16x32_bf16 v[62:65], v[62:65], v[14:17], 0
	s_lshl_b32 s4, s8, 1
	s_add_u32 s2, s2, s4
	s_addc_u32 s3, s3, 0
	s_waitcnt lgkmcnt(0)
	v_mfma_f32_16x16x32_bf16 v[62:65], v[110:113], v[10:13], v[62:65]
	ds_read_b128 v[110:113], v0 offset:128
	s_waitcnt lgkmcnt(0)
	v_mfma_f32_16x16x32_bf16 v[62:65], v[110:113], v[6:9], v[62:65]
	ds_read_b128 v[110:113], v0 offset:192
	s_waitcnt lgkmcnt(0)
	v_mfma_f32_16x16x32_bf16 v[62:65], v[110:113], v[2:5], v[62:65]
	s_nop 7
	v_fma_f32 v62, v72, v109, v62
	v_mul_f32_e32 v109, 0x3d372713, v62
	v_mul_f32_e32 v109, v62, v109
	v_fma_f32 v109, v62, v109, v62
	v_mul_f32_e32 v109, 0x3f4c422a, v109
	v_add_f32_e32 v109, v109, v109
	v_mul_f32_e32 v109, 0x3fb8aa3b, v109
	v_exp_f32_e32 v109, v109
	v_mul_f32_e32 v62, 0.5, v62
	v_add_f32_e32 v109, 1.0, v109
	v_div_scale_f32 v110, s[4:5], v109, v109, 2.0
	v_rcp_f32_e32 v111, v110
	s_nop 0
	v_fma_f32 v112, -v110, v111, 1.0
	v_fmac_f32_e32 v111, v112, v111
	v_div_scale_f32 v112, vcc, 2.0, v109, 2.0
	v_mul_f32_e32 v113, v112, v111
	v_fma_f32 v114, -v110, v113, v112
	v_fmac_f32_e32 v113, v114, v111
	v_fma_f32 v110, -v110, v113, v112
	v_div_fmas_f32 v110, v110, v111, v113
	v_div_fixup_f32 v109, v110, v109, 2.0
	v_sub_f32_e32 v109, 1.0, v109
	v_add_f32_e32 v109, 1.0, v109
	v_mul_f32_e32 v62, v62, v109
	v_cvt_pk_bf16_f32 v62, v62, s0
	global_store_short v108, v62, s[2:3]
	s_waitcnt vmcnt(15)
	v_lshlrev_b32_e32 v62, 16, v104
	v_fma_f32 v62, v72, v62, v63
	v_mul_f32_e32 v63, 0x3d372713, v62
	v_mul_f32_e32 v63, v62, v63
	v_fma_f32 v63, v62, v63, v62
	v_mul_f32_e32 v63, 0x3f4c422a, v63
	v_add_f32_e32 v63, v63, v63
	v_mul_f32_e32 v63, 0x3fb8aa3b, v63
	v_exp_f32_e32 v63, v63
	v_mul_f32_e32 v62, 0.5, v62
	v_add_f32_e32 v63, 1.0, v63
	v_div_scale_f32 v104, s[4:5], v63, v63, 2.0
	v_rcp_f32_e32 v108, v104
	s_nop 0
	v_fma_f32 v109, -v104, v108, 1.0
	v_fmac_f32_e32 v108, v109, v108
	v_div_scale_f32 v109, vcc, 2.0, v63, 2.0
	v_mul_f32_e32 v110, v109, v108
	v_fma_f32 v111, -v104, v110, v109
	v_fmac_f32_e32 v110, v111, v108
	v_fma_f32 v104, -v104, v110, v109
	v_div_fmas_f32 v104, v104, v108, v110
	v_div_fixup_f32 v63, v104, v63, 2.0
	v_sub_f32_e32 v63, 1.0, v63
	v_add_f32_e32 v63, 1.0, v63
	v_mul_f32_e32 v62, v62, v63
	v_cvt_pk_bf16_f32 v62, v62, s0
	global_store_short v103, v62, s[2:3]
	s_waitcnt vmcnt(15)
; DI u16 f2bf(float x) { return (u16)(pk2(x, 0.f) & 0xffffu); }
; DI float bf2f(u16 h) { return __uint_as_float(((unsigned)h) << 16); }
; DI f32x4 mfma16(bf16x8 a, bf16x8 b, f32x4 c) { return __builtin_amdgcn_mfma_f32_16x16x32_bf16(a, b, c, 0, 0, 0); }
; template <bool OUT>
; DI void s5_item(int wv0, PP p, int item, unsigned char* smem) {
;     ...
;   for (int sub = 0; sub < 4; ++sub) {
;     const bf16x8 ua = uall[sub];
; #pragma unroll
;     for (int nt = 0; nt < 8; ++nt) {
;       const f32x4 a = mfma16(ua, bb[nt], f32x4{0.f, 0.f, 0.f, 0.f});
; #pragma unroll
;       for (int j = 0; j < 4; ++j) sBU[(4 * fq + j) * 132 + 16 * nt + fr] = a[j];
;     }
;     __syncthreads();
; #pragma unroll 4
;     for (int t = 0; t < 16; ++t) {
;       const float bur = sBU[t * 132 + lane], bui = sBU[t * 132 + 64 + lane];
;       const float nr = lbr * hr - lbi * hi + bur;
;       const float nim = lbr * hi + lbi * hr + bui;
;       hr = nr;
;       hi = nim;
;       if (OUT) {
;         sH[t * 136 + lane] = f2bf(hr);
;         sH[t * 136 + 64 + lane] = f2bf(hi);
;       }
;     }
;     __syncthreads();
;     if (OUT) {
;       f32x4 y = {0.f, 0.f, 0.f, 0.f};
; #pragma unroll
;       for (int ks = 0; ks < 4; ++ks) y = mfma16(*(const bf16x8*)(sH + fr * 136 + 32 * ks + 8 * fq), cf[ks], y);
; #pragma unroll
;       for (int j = 0; j < 4; ++j) {
;         const size_t o = (size_t)(sub * 16 + 4 * fq + j) * 512 + fr;
;         YS[o] = f2bf(gelu_t(y[j] + dk * bf2f(usk[sub][j])));
;       }
;       __syncthreads();
	v_lshlrev_b32_e32 v62, 16, v102
	v_fma_f32 v62, v72, v62, v64
	v_mul_f32_e32 v63, 0x3d372713, v62
	v_mul_f32_e32 v63, v62, v63
	v_fma_f32 v63, v62, v63, v62
	v_mul_f32_e32 v63, 0x3f4c422a, v63
	v_add_f32_e32 v63, v63, v63
	v_mul_f32_e32 v63, 0x3fb8aa3b, v63
	v_exp_f32_e32 v63, v63
	v_mul_f32_e32 v62, 0.5, v62
	v_add_f32_e32 v63, 1.0, v63
	v_div_scale_f32 v64, s[4:5], v63, v63, 2.0
	v_rcp_f32_e32 v102, v64
	s_nop 0
	v_fma_f32 v103, -v64, v102, 1.0
	v_fmac_f32_e32 v102, v103, v102
	v_div_scale_f32 v103, vcc, 2.0, v63, 2.0
	v_mul_f32_e32 v104, v103, v102
	v_fma_f32 v108, -v64, v104, v103
	v_fmac_f32_e32 v104, v108, v102
	v_fma_f32 v64, -v64, v104, v103
	v_div_fmas_f32 v64, v64, v102, v104
	v_div_fixup_f32 v63, v64, v63, 2.0
	v_sub_f32_e32 v63, 1.0, v63
	v_add_f32_e32 v63, 1.0, v63
	v_mul_f32_e32 v62, v62, v63
	v_cvt_pk_bf16_f32 v62, v62, s0
	global_store_short v101, v62, s[2:3]
	s_waitcnt vmcnt(15)
	v_lshlrev_b32_e32 v62, 16, v100
	v_fmac_f32_e32 v65, v72, v62
	v_mul_f32_e32 v62, 0x3d372713, v65
	v_mul_f32_e32 v62, v65, v62
	v_fma_f32 v62, v65, v62, v65
	v_mul_f32_e32 v62, 0x3f4c422a, v62
	v_add_f32_e32 v62, v62, v62
	v_mul_f32_e32 v62, 0x3fb8aa3b, v62
	v_exp_f32_e32 v62, v62
	s_nop 0
	v_add_f32_e32 v62, 1.0, v62
	v_div_scale_f32 v63, s[4:5], v62, v62, 2.0
	v_rcp_f32_e32 v64, v63
	s_mov_b32 s4, 16
	v_fma_f32 v100, -v63, v64, 1.0
	v_fmac_f32_e32 v64, v100, v64
	v_div_scale_f32 v100, vcc, 2.0, v62, 2.0
	v_mul_f32_e32 v101, v100, v64
	v_fma_f32 v102, -v63, v101, v100
	v_fmac_f32_e32 v101, v102, v64
	v_fma_f32 v63, -v63, v101, v100
	v_div_fmas_f32 v63, v63, v64, v101
	v_div_fixup_f32 v62, v63, v62, 2.0
	v_sub_f32_e32 v62, 1.0, v62
	v_mul_f32_e32 v63, 0.5, v65
	v_add_f32_e32 v62, 1.0, v62
	v_mfma_f32_16x16x32_bf16 v[100:103], v[58:61], v[26:29], 0
	v_mul_f32_e32 v62, v63, v62
	v_cvt_pk_bf16_f32 v62, v62, s0
	global_store_short v99, v62, s[2:3]
	v_add_u32_e32 v63, v105, v106
	v_add_u32_e32 v62, v105, v107
	s_barrier
	s_nop 1
	ds_write_b32 v63, v100 offset:8192
	ds_write_b32 v62, v101 offset:8192
	ds_write_b32 v62, v102 offset:8720
	ds_write_b32 v62, v103 offset:9248
	v_mfma_f32_16x16x32_bf16 v[100:103], v[58:61], v[22:25], 0
	s_nop 7
	ds_write_b32 v63, v100 offset:8256
	ds_write_b32 v62, v101 offset:8256
	ds_write_b32 v62, v102 offset:8784
	ds_write_b32 v62, v103 offset:9312
	v_mfma_f32_16x16x32_bf16 v[100:103], v[58:61], v[34:37], 0
	s_nop 7
	ds_write_b32 v63, v100 offset:8320
	ds_write_b32 v62, v101 offset:8320
	ds_write_b32 v62, v102 offset:8848
	ds_write_b32 v62, v103 offset:9376
	v_mfma_f32_16x16x32_bf16 v[100:103], v[58:61], v[30:33], 0
	s_nop 7
	ds_write_b32 v63, v100 offset:8384
	ds_write_b32 v62, v101 offset:8384
	ds_write_b32 v62, v102 offset:8912
	ds_write_b32 v62, v103 offset:9440
	v_mfma_f32_16x16x32_bf16 v[100:103], v[58:61], v[42:45], 0
	s_nop 7
	ds_write_b32 v63, v100 offset:8448
	ds_write_b32 v62, v101 offset:8448
	ds_write_b32 v62, v102 offset:8976
	ds_write_b32 v62, v103 offset:9504
	v_mfma_f32_16x16x32_bf16 v[100:103], v[58:61], v[38:41], 0
	s_nop 7
	ds_write_b32 v63, v100 offset:8512
	ds_write_b32 v62, v101 offset:8512
	ds_write_b32 v62, v102 offset:9040
	ds_write_b32 v62, v103 offset:9568
	v_mfma_f32_16x16x32_bf16 v[100:103], v[58:61], v[50:53], 0
	s_nop 7
	ds_write_b32 v63, v100 offset:8576
	ds_write_b32 v62, v101 offset:8576
	ds_write_b32 v62, v102 offset:9104
	ds_write_b32 v62, v103 offset:9632
	v_mfma_f32_16x16x32_bf16 v[58:61], v[58:61], v[46:49], 0
	s_nop 7
	ds_write_b32 v63, v58 offset:8640
	ds_write_b32 v62, v59 offset:8640
	ds_write_b32 v62, v60 offset:9168
	ds_write_b32 v62, v61 offset:9696
	v_mov_b32_e32 v58, v82
	v_mov_b32_e32 v59, v81
	s_waitcnt lgkmcnt(0)
	s_barrier
.LBB0_786:
	v_add_u32_e32 v117, 32, v58
	v_add_u32_e32 v118, 1088, v58
	v_add_u32_e32 v119, 2144, v58
	v_add_u32_e32 v120, 3200, v58
	v_add_u32_e32 v121, 4256, v58
	v_add_u32_e32 v122, 5312, v58
	v_add_u32_e32 v123, 6368, v58
	v_add_u32_e32 v124, 7424, v58
	ds_read2st64_b32 v[152:153], v117 offset1:1
	ds_read2_b32 v[154:155], v117 offset0:132 offset1:196
	ds_read2st64_b32 v[156:157], v118 offset1:1
	ds_read2_b32 v[158:159], v118 offset0:132 offset1:196
	ds_read2st64_b32 v[160:161], v119 offset1:1
	ds_read2_b32 v[162:163], v119 offset0:132 offset1:196
	ds_read2st64_b32 v[164:165], v120 offset1:1
	ds_read2_b32 v[166:167], v120 offset0:132 offset1:196
	ds_read2st64_b32 v[168:169], v121 offset1:1
	ds_read2_b32 v[170:171], v121 offset0:132 offset1:196
	ds_read2st64_b32 v[172:173], v122 offset1:1
	ds_read2_b32 v[174:175], v122 offset0:132 offset1:196
	ds_read2st64_b32 v[176:177], v123 offset1:1
	ds_read2_b32 v[178:179], v123 offset0:132 offset1:196
	ds_read2st64_b32 v[180:181], v124 offset1:1
	ds_read2_b32 v[182:183], v124 offset0:132 offset1:196
	v_add_u32_e32 v126, 0x12820, v59
	s_waitcnt lgkmcnt(0)
; DI u16 f2bf(float x) { return (u16)(pk2(x, 0.f) & 0xffffu); }
; template <bool OUT>
; DI void s5_item(int wv0, PP p, int item, unsigned char* smem) {
;     ...
;     for (int t = 0; t < 16; ++t) {
;       const float bur = sBU[t * 132 + lane], bui = sBU[t * 132 + 64 + lane];
;       const float nr = lbr * hr - lbi * hi + bur;
;       const float nim = lbr * hi + lbi * hr + bui;
;       hr = nr;
;       hi = nim;
;       if (OUT) {
;         sH[t * 136 + lane] = f2bf(hr);
;         sH[t * 136 + 64 + lane] = f2bf(hi);
;       }
;     }
	v_pk_mul_f32 v[184:185], v[70:71], v[68:69] op_sel:[0,1]
	v_pk_fma_f32 v[186:187], v[66:67], v[68:69], v[184:185] neg_lo:[0,0,1] neg_hi:[0,0,1]
	v_pk_fma_f32 v[188:189], v[66:67], v[68:69], v[184:185] op_sel_hi:[1,0,1]
	v_mov_b32_e32 v187, v189
	v_pk_add_f32 v[192:193], v[186:187], v[152:153]
	v_cvt_pk_bf16_f32 v190, v192, s0
	ds_write_b16 v126, v190
	v_cvt_pk_bf16_f32 v191, v193, s0
	ds_write_b16 v126, v191 offset:128
	v_pk_mul_f32 v[184:185], v[70:71], v[192:193] op_sel:[0,1]
	v_pk_fma_f32 v[186:187], v[66:67], v[192:193], v[184:185] neg_lo:[0,0,1] neg_hi:[0,0,1]
	v_pk_fma_f32 v[188:189], v[66:67], v[192:193], v[184:185] op_sel_hi:[1,0,1]
	v_mov_b32_e32 v187, v189
	v_pk_add_f32 v[68:69], v[186:187], v[154:155]
	v_cvt_pk_bf16_f32 v190, v68, s0
	ds_write_b16 v126, v190 offset:272
	v_cvt_pk_bf16_f32 v191, v69, s0
	ds_write_b16 v126, v191 offset:400
	v_pk_mul_f32 v[184:185], v[70:71], v[68:69] op_sel:[0,1]
	v_pk_fma_f32 v[186:187], v[66:67], v[68:69], v[184:185] neg_lo:[0,0,1] neg_hi:[0,0,1]
	v_pk_fma_f32 v[188:189], v[66:67], v[68:69], v[184:185] op_sel_hi:[1,0,1]
	v_mov_b32_e32 v187, v189
	v_pk_add_f32 v[192:193], v[186:187], v[156:157]
	v_cvt_pk_bf16_f32 v190, v192, s0
	ds_write_b16 v126, v190 offset:544
	v_cvt_pk_bf16_f32 v191, v193, s0
	ds_write_b16 v126, v191 offset:672
	v_pk_mul_f32 v[184:185], v[70:71], v[192:193] op_sel:[0,1]
	v_pk_fma_f32 v[186:187], v[66:67], v[192:193], v[184:185] neg_lo:[0,0,1] neg_hi:[0,0,1]
	v_pk_fma_f32 v[188:189], v[66:67], v[192:193], v[184:185] op_sel_hi:[1,0,1]
	v_mov_b32_e32 v187, v189
	v_pk_add_f32 v[68:69], v[186:187], v[158:159]
	v_cvt_pk_bf16_f32 v190, v68, s0
	ds_write_b16 v126, v190 offset:816
	v_cvt_pk_bf16_f32 v191, v69, s0
	ds_write_b16 v126, v191 offset:944
	v_pk_mul_f32 v[184:185], v[70:71], v[68:69] op_sel:[0,1]
	v_pk_fma_f32 v[186:187], v[66:67], v[68:69], v[184:185] neg_lo:[0,0,1] neg_hi:[0,0,1]
	v_pk_fma_f32 v[188:189], v[66:67], v[68:69], v[184:185] op_sel_hi:[1,0,1]
	v_mov_b32_e32 v187, v189
	v_pk_add_f32 v[192:193], v[186:187], v[160:161]
	v_cvt_pk_bf16_f32 v190, v192, s0
	ds_write_b16 v126, v190 offset:1088
	v_cvt_pk_bf16_f32 v191, v193, s0
	ds_write_b16 v126, v191 offset:1216
	v_pk_mul_f32 v[184:185], v[70:71], v[192:193] op_sel:[0,1]
	v_pk_fma_f32 v[186:187], v[66:67], v[192:193], v[184:185] neg_lo:[0,0,1] neg_hi:[0,0,1]
	v_pk_fma_f32 v[188:189], v[66:67], v[192:193], v[184:185] op_sel_hi:[1,0,1]
	v_mov_b32_e32 v187, v189
	v_pk_add_f32 v[68:69], v[186:187], v[162:163]
	v_cvt_pk_bf16_f32 v190, v68, s0
	ds_write_b16 v126, v190 offset:1360
	v_cvt_pk_bf16_f32 v191, v69, s0
	ds_write_b16 v126, v191 offset:1488
	v_pk_mul_f32 v[184:185], v[70:71], v[68:69] op_sel:[0,1]
	v_pk_fma_f32 v[186:187], v[66:67], v[68:69], v[184:185] neg_lo:[0,0,1] neg_hi:[0,0,1]
	v_pk_fma_f32 v[188:189], v[66:67], v[68:69], v[184:185] op_sel_hi:[1,0,1]
	v_mov_b32_e32 v187, v189
	v_pk_add_f32 v[192:193], v[186:187], v[164:165]
	v_cvt_pk_bf16_f32 v190, v192, s0
	ds_write_b16 v126, v190 offset:1632
	v_cvt_pk_bf16_f32 v191, v193, s0
	ds_write_b16 v126, v191 offset:1760
	v_pk_mul_f32 v[184:185], v[70:71], v[192:193] op_sel:[0,1]
	v_pk_fma_f32 v[186:187], v[66:67], v[192:193], v[184:185] neg_lo:[0,0,1] neg_hi:[0,0,1]
	v_pk_fma_f32 v[188:189], v[66:67], v[192:193], v[184:185] op_sel_hi:[1,0,1]
	v_mov_b32_e32 v187, v189
	v_pk_add_f32 v[68:69], v[186:187], v[166:167]
	v_cvt_pk_bf16_f32 v190, v68, s0
	ds_write_b16 v126, v190 offset:1904
	v_cvt_pk_bf16_f32 v191, v69, s0
	ds_write_b16 v126, v191 offset:2032
	v_pk_mul_f32 v[184:185], v[70:71], v[68:69] op_sel:[0,1]
	v_pk_fma_f32 v[186:187], v[66:67], v[68:69], v[184:185] neg_lo:[0,0,1] neg_hi:[0,0,1]
	v_pk_fma_f32 v[188:189], v[66:67], v[68:69], v[184:185] op_sel_hi:[1,0,1]
	v_mov_b32_e32 v187, v189
	v_pk_add_f32 v[192:193], v[186:187], v[168:169]
	v_cvt_pk_bf16_f32 v190, v192, s0
	ds_write_b16 v126, v190 offset:2176
	v_cvt_pk_bf16_f32 v191, v193, s0
	ds_write_b16 v126, v191 offset:2304
	v_pk_mul_f32 v[184:185], v[70:71], v[192:193] op_sel:[0,1]
	v_pk_fma_f32 v[186:187], v[66:67], v[192:193], v[184:185] neg_lo:[0,0,1] neg_hi:[0,0,1]
	v_pk_fma_f32 v[188:189], v[66:67], v[192:193], v[184:185] op_sel_hi:[1,0,1]
	v_mov_b32_e32 v187, v189
	v_pk_add_f32 v[68:69], v[186:187], v[170:171]
	v_cvt_pk_bf16_f32 v190, v68, s0
	ds_write_b16 v126, v190 offset:2448
	v_cvt_pk_bf16_f32 v191, v69, s0
	ds_write_b16 v126, v191 offset:2576
	v_pk_mul_f32 v[184:185], v[70:71], v[68:69] op_sel:[0,1]
	v_pk_fma_f32 v[186:187], v[66:67], v[68:69], v[184:185] neg_lo:[0,0,1] neg_hi:[0,0,1]
	v_pk_fma_f32 v[188:189], v[66:67], v[68:69], v[184:185] op_sel_hi:[1,0,1]
	v_mov_b32_e32 v187, v189
	v_pk_add_f32 v[192:193], v[186:187], v[172:173]
	v_cvt_pk_bf16_f32 v190, v192, s0
	ds_write_b16 v126, v190 offset:2720
	v_cvt_pk_bf16_f32 v191, v193, s0
	ds_write_b16 v126, v191 offset:2848
	v_pk_mul_f32 v[184:185], v[70:71], v[192:193] op_sel:[0,1]
	v_pk_fma_f32 v[186:187], v[66:67], v[192:193], v[184:185] neg_lo:[0,0,1] neg_hi:[0,0,1]
	v_pk_fma_f32 v[188:189], v[66:67], v[192:193], v[184:185] op_sel_hi:[1,0,1]
	v_mov_b32_e32 v187, v189
	v_pk_add_f32 v[68:69], v[186:187], v[174:175]
	v_cvt_pk_bf16_f32 v190, v68, s0
	ds_write_b16 v126, v190 offset:2992
	v_cvt_pk_bf16_f32 v191, v69, s0
	ds_write_b16 v126, v191 offset:3120
	v_pk_mul_f32 v[184:185], v[70:71], v[68:69] op_sel:[0,1]
	v_pk_fma_f32 v[186:187], v[66:67], v[68:69], v[184:185] neg_lo:[0,0,1] neg_hi:[0,0,1]
	v_pk_fma_f32 v[188:189], v[66:67], v[68:69], v[184:185] op_sel_hi:[1,0,1]
	v_mov_b32_e32 v187, v189
	v_pk_add_f32 v[192:193], v[186:187], v[176:177]
	v_cvt_pk_bf16_f32 v190, v192, s0
	ds_write_b16 v126, v190 offset:3264
	v_cvt_pk_bf16_f32 v191, v193, s0
	ds_write_b16 v126, v191 offset:3392
	v_pk_mul_f32 v[184:185], v[70:71], v[192:193] op_sel:[0,1]
	v_pk_fma_f32 v[186:187], v[66:67], v[192:193], v[184:185] neg_lo:[0,0,1] neg_hi:[0,0,1]
	v_pk_fma_f32 v[188:189], v[66:67], v[192:193], v[184:185] op_sel_hi:[1,0,1]
	v_mov_b32_e32 v187, v189
	v_pk_add_f32 v[68:69], v[186:187], v[178:179]
	v_cvt_pk_bf16_f32 v190, v68, s0
	ds_write_b16 v126, v190 offset:3536
	v_cvt_pk_bf16_f32 v191, v69, s0
	ds_write_b16 v126, v191 offset:3664
	v_pk_mul_f32 v[184:185], v[70:71], v[68:69] op_sel:[0,1]
	v_pk_fma_f32 v[186:187], v[66:67], v[68:69], v[184:185] neg_lo:[0,0,1] neg_hi:[0,0,1]
	v_pk_fma_f32 v[188:189], v[66:67], v[68:69], v[184:185] op_sel_hi:[1,0,1]
	v_mov_b32_e32 v187, v189
	v_pk_add_f32 v[192:193], v[186:187], v[180:181]
	v_cvt_pk_bf16_f32 v190, v192, s0
	ds_write_b16 v126, v190 offset:3808
	v_cvt_pk_bf16_f32 v191, v193, s0
	ds_write_b16 v126, v191 offset:3936
	v_pk_mul_f32 v[184:185], v[70:71], v[192:193] op_sel:[0,1]
	v_pk_fma_f32 v[186:187], v[66:67], v[192:193], v[184:185] neg_lo:[0,0,1] neg_hi:[0,0,1]
	v_pk_fma_f32 v[188:189], v[66:67], v[192:193], v[184:185] op_sel_hi:[1,0,1]
	v_mov_b32_e32 v187, v189
	v_pk_add_f32 v[68:69], v[186:187], v[182:183]
	v_cvt_pk_bf16_f32 v190, v68, s0
	ds_write_b16 v126, v190 offset:4080
	v_cvt_pk_bf16_f32 v191, v69, s0
	ds_write_b16 v126, v191 offset:4208
	s_waitcnt lgkmcnt(0)
	s_barrier
; DI u16 f2bf(float x) { return (u16)(pk2(x, 0.f) & 0xffffu); }
; DI float bf2f(u16 h) { return __uint_as_float(((unsigned)h) << 16); }
; DI f32x4 mfma16(bf16x8 a, bf16x8 b, f32x4 c) { return __builtin_amdgcn_mfma_f32_16x16x32_bf16(a, b, c, 0, 0, 0); }
; template <bool OUT>
; DI void s5_item(int wv0, PP p, int item, unsigned char* smem) {
;     ...
;   for (int sub = 0; sub < 4; ++sub) {
;     const bf16x8 ua = uall[sub];
; #pragma unroll
;     for (int nt = 0; nt < 8; ++nt) {
;       const f32x4 a = mfma16(ua, bb[nt], f32x4{0.f, 0.f, 0.f, 0.f});
; #pragma unroll
;       for (int j = 0; j < 4; ++j) sBU[(4 * fq + j) * 132 + 16 * nt + fr] = a[j];
;     }
;     __syncthreads();
; #pragma unroll 4
;     for (int t = 0; t < 16; ++t) {
;       const float bur = sBU[t * 132 + lane], bui = sBU[t * 132 + 64 + lane];
;       const float nr = lbr * hr - lbi * hi + bur;
;       const float nim = lbr * hi + lbi * hr + bui;
;       hr = nr;
;       hi = nim;
;       if (OUT) {
;         sH[t * 136 + lane] = f2bf(hr);
;         sH[t * 136 + 64 + lane] = f2bf(hi);
;       }
;     }
;     __syncthreads();
;     if (OUT) {
;       f32x4 y = {0.f, 0.f, 0.f, 0.f};
; #pragma unroll
;       for (int ks = 0; ks < 4; ++ks) y = mfma16(*(const bf16x8*)(sH + fr * 136 + 32 * ks + 8 * fq), cf[ks], y);
; #pragma unroll
;       for (int j = 0; j < 4; ++j) {
;         const size_t o = (size_t)(sub * 16 + 4 * fq + j) * 512 + fr;
;         YS[o] = f2bf(gelu_t(y[j] + dk * bf2f(usk[sub][j])));
;       }
;       __syncthreads();
	ds_read_b128 v[58:61], v0
	ds_read_b128 v[100:103], v0 offset:64
	s_waitcnt vmcnt(15)
	v_lshlrev_b32_e32 v64, 16, v98
	s_waitcnt lgkmcnt(1)
	v_mfma_f32_16x16x32_bf16 v[58:61], v[58:61], v[14:17], 0
	s_waitcnt lgkmcnt(0)
	v_mfma_f32_16x16x32_bf16 v[58:61], v[100:103], v[10:13], v[58:61]
	ds_read_b128 v[100:103], v0 offset:128
	s_waitcnt lgkmcnt(0)
	v_mfma_f32_16x16x32_bf16 v[58:61], v[100:103], v[6:9], v[58:61]
	ds_read_b128 v[100:103], v0 offset:192
	s_waitcnt lgkmcnt(0)
	v_mfma_f32_16x16x32_bf16 v[58:61], v[100:103], v[2:5], v[58:61]
	s_nop 7
	v_fma_f32 v58, v72, v64, v58
	v_mul_f32_e32 v64, 0x3d372713, v58
	v_mul_f32_e32 v64, v58, v64
	v_fma_f32 v64, v58, v64, v58
	v_mul_f32_e32 v64, 0x3f4c422a, v64
	v_add_f32_e32 v64, v64, v64
	v_mul_f32_e32 v64, 0x3fb8aa3b, v64
	v_exp_f32_e32 v64, v64
	v_mul_f32_e32 v58, 0.5, v58
	v_add_f32_e32 v64, 1.0, v64
	v_div_scale_f32 v65, s[4:5], v64, v64, 2.0
	v_rcp_f32_e32 v98, v65
	s_nop 0
	v_fma_f32 v99, -v65, v98, 1.0
	v_fmac_f32_e32 v98, v99, v98
	v_div_scale_f32 v99, vcc, 2.0, v64, 2.0
	v_mul_f32_e32 v100, v99, v98
	v_fma_f32 v101, -v65, v100, v99
	v_fmac_f32_e32 v100, v101, v98
	v_fma_f32 v65, -v65, v100, v99
	v_div_fmas_f32 v65, v65, v98, v100
	v_div_fixup_f32 v64, v65, v64, 2.0
	v_sub_f32_e32 v64, 1.0, v64
	v_add_f32_e32 v64, 1.0, v64
	v_mul_f32_e32 v58, v58, v64
	v_cvt_pk_bf16_f32 v58, v58, s0
	global_store_short v97, v58, s[2:3]
	s_waitcnt vmcnt(15)
	v_lshlrev_b32_e32 v58, 16, v96
	v_fma_f32 v58, v72, v58, v59
	v_mul_f32_e32 v59, 0x3d372713, v58
	v_mul_f32_e32 v59, v58, v59
	v_fma_f32 v59, v58, v59, v58
	v_mul_f32_e32 v59, 0x3f4c422a, v59
	v_add_f32_e32 v59, v59, v59
	v_mul_f32_e32 v59, 0x3fb8aa3b, v59
	v_exp_f32_e32 v59, v59
	v_mul_f32_e32 v58, 0.5, v58
	v_add_f32_e32 v59, 1.0, v59
	v_div_scale_f32 v64, s[4:5], v59, v59, 2.0
	v_rcp_f32_e32 v65, v64
	s_nop 0
	v_fma_f32 v96, -v64, v65, 1.0
	v_fmac_f32_e32 v65, v96, v65
	v_div_scale_f32 v96, vcc, 2.0, v59, 2.0
	v_mul_f32_e32 v97, v96, v65
	v_fma_f32 v98, -v64, v97, v96
	v_fmac_f32_e32 v97, v98, v65
	v_fma_f32 v64, -v64, v97, v96
	v_div_fmas_f32 v64, v64, v65, v97
	v_div_fixup_f32 v59, v64, v59, 2.0
	v_sub_f32_e32 v59, 1.0, v59
	v_add_f32_e32 v59, 1.0, v59
	v_mul_f32_e32 v58, v58, v59
	v_cvt_pk_bf16_f32 v58, v58, s0
	global_store_short v95, v58, s[2:3]
	s_waitcnt vmcnt(15)
	v_lshlrev_b32_e32 v58, 16, v94
	v_fma_f32 v58, v72, v58, v60
	v_mul_f32_e32 v59, 0x3d372713, v58
	v_mul_f32_e32 v59, v58, v59
	v_fma_f32 v59, v58, v59, v58
	v_mul_f32_e32 v59, 0x3f4c422a, v59
	v_add_f32_e32 v59, v59, v59
	v_mul_f32_e32 v59, 0x3fb8aa3b, v59
	v_exp_f32_e32 v59, v59
	v_mul_f32_e32 v58, 0.5, v58
	v_add_f32_e32 v59, 1.0, v59
	v_div_scale_f32 v60, s[4:5], v59, v59, 2.0
	v_rcp_f32_e32 v64, v60
	s_nop 0
	v_fma_f32 v65, -v60, v64, 1.0
	v_fmac_f32_e32 v64, v65, v64
	v_div_scale_f32 v65, vcc, 2.0, v59, 2.0
	v_mul_f32_e32 v94, v65, v64
	v_fma_f32 v95, -v60, v94, v65
	v_fmac_f32_e32 v94, v95, v64
	v_fma_f32 v60, -v60, v94, v65
	v_div_fmas_f32 v60, v60, v64, v94
	v_div_fixup_f32 v59, v60, v59, 2.0
	v_sub_f32_e32 v59, 1.0, v59
	v_add_f32_e32 v59, 1.0, v59
	v_mul_f32_e32 v58, v58, v59
	v_cvt_pk_bf16_f32 v58, v58, s0
	global_store_short v93, v58, s[2:3]
	s_waitcnt vmcnt(15)
	v_lshlrev_b32_e32 v58, 16, v92
	v_fmac_f32_e32 v61, v72, v58
	v_mul_f32_e32 v58, 0x3d372713, v61
	v_mul_f32_e32 v58, v61, v58
	v_fma_f32 v58, v61, v58, v61
	v_mul_f32_e32 v58, 0x3f4c422a, v58
	v_add_f32_e32 v58, v58, v58
	v_mul_f32_e32 v58, 0x3fb8aa3b, v58
	v_exp_f32_e32 v58, v58
	s_nop 0
	v_add_f32_e32 v58, 1.0, v58
	v_div_scale_f32 v59, s[4:5], v58, v58, 2.0
	v_rcp_f32_e32 v60, v59
	s_mov_b32 s4, 16
	v_fma_f32 v64, -v59, v60, 1.0
	v_fmac_f32_e32 v60, v64, v60
	v_div_scale_f32 v64, vcc, 2.0, v58, 2.0
	v_mul_f32_e32 v65, v64, v60
	v_fma_f32 v92, -v59, v65, v64
	v_fmac_f32_e32 v65, v92, v60
	v_fma_f32 v59, -v59, v65, v64
	v_div_fmas_f32 v59, v59, v60, v65
	v_div_fixup_f32 v58, v59, v58, 2.0
	v_sub_f32_e32 v58, 1.0, v58
	v_mul_f32_e32 v59, 0.5, v61
	v_add_f32_e32 v58, 1.0, v58
	v_mul_f32_e32 v58, v59, v58
	v_cvt_pk_bf16_f32 v58, v58, s0
	global_store_short v91, v58, s[2:3]
	v_mfma_f32_16x16x32_bf16 v[58:61], v[54:57], v[26:29], 0
	s_barrier
	s_nop 6
	ds_write_b32 v63, v58 offset:8192
	ds_write_b32 v62, v59 offset:8192
	ds_write_b32 v62, v60 offset:8720
	ds_write_b32 v62, v61 offset:9248
	v_mfma_f32_16x16x32_bf16 v[58:61], v[54:57], v[22:25], 0
	s_nop 7
	ds_write_b32 v63, v58 offset:8256
	ds_write_b32 v62, v59 offset:8256
	ds_write_b32 v62, v60 offset:8784
	ds_write_b32 v62, v61 offset:9312
	v_mfma_f32_16x16x32_bf16 v[58:61], v[54:57], v[34:37], 0
	s_nop 7
	ds_write_b32 v63, v58 offset:8320
	ds_write_b32 v62, v59 offset:8320
	ds_write_b32 v62, v60 offset:8848
	ds_write_b32 v62, v61 offset:9376
	v_mfma_f32_16x16x32_bf16 v[58:61], v[54:57], v[30:33], 0
	s_nop 7
	ds_write_b32 v63, v58 offset:8384
	ds_write_b32 v62, v59 offset:8384
	ds_write_b32 v62, v60 offset:8912
	ds_write_b32 v62, v61 offset:9440
	v_mfma_f32_16x16x32_bf16 v[58:61], v[54:57], v[42:45], 0
	s_nop 7
	ds_write_b32 v63, v58 offset:8448
	ds_write_b32 v62, v59 offset:8448
	ds_write_b32 v62, v60 offset:8976
	ds_write_b32 v62, v61 offset:9504
	v_mfma_f32_16x16x32_bf16 v[58:61], v[54:57], v[38:41], 0
	s_nop 7
	ds_write_b32 v63, v58 offset:8512
	ds_write_b32 v62, v59 offset:8512
	ds_write_b32 v62, v60 offset:9040
	ds_write_b32 v62, v61 offset:9568
	v_mfma_f32_16x16x32_bf16 v[58:61], v[54:57], v[50:53], 0
	s_nop 7
	ds_write_b32 v63, v58 offset:8576
	ds_write_b32 v62, v59 offset:8576
	ds_write_b32 v62, v60 offset:9104
	ds_write_b32 v62, v61 offset:9632
	v_mfma_f32_16x16x32_bf16 v[54:57], v[54:57], v[46:49], 0
	s_nop 7
	ds_write_b32 v63, v54 offset:8640
	ds_write_b32 v62, v55 offset:8640
	ds_write_b32 v62, v56 offset:9168
	ds_write_b32 v62, v57 offset:9696
	v_mov_b32_e32 v54, v82
	v_mov_b32_e32 v55, v81
	s_waitcnt lgkmcnt(0)
	s_barrier
; DI u16 f2bf(float x) { return (u16)(pk2(x, 0.f) & 0xffffu); }
; template <bool OUT>
; DI void s5_item(int wv0, PP p, int item, unsigned char* smem) {
;     ...
;     for (int t = 0; t < 16; ++t) {
;       const float bur = sBU[t * 132 + lane], bui = sBU[t * 132 + 64 + lane];
;       const float nr = lbr * hr - lbi * hi + bur;
;       const float nim = lbr * hi + lbi * hr + bui;
;       hr = nr;
;       hi = nim;
;       if (OUT) {
;         sH[t * 136 + lane] = f2bf(hr);
;         sH[t * 136 + 64 + lane] = f2bf(hi);
;       }
;     }
.LBB0_788:
	v_add_u32_e32 v117, 32, v54
	v_add_u32_e32 v118, 1088, v54
	v_add_u32_e32 v119, 2144, v54
	v_add_u32_e32 v120, 3200, v54
	v_add_u32_e32 v121, 4256, v54
	v_add_u32_e32 v122, 5312, v54
	v_add_u32_e32 v123, 6368, v54
	v_add_u32_e32 v124, 7424, v54
	ds_read2st64_b32 v[152:153], v117 offset1:1
	ds_read2_b32 v[154:155], v117 offset0:132 offset1:196
	ds_read2st64_b32 v[156:157], v118 offset1:1
	ds_read2_b32 v[158:159], v118 offset0:132 offset1:196
	ds_read2st64_b32 v[160:161], v119 offset1:1
	ds_read2_b32 v[162:163], v119 offset0:132 offset1:196
	ds_read2st64_b32 v[164:165], v120 offset1:1
	ds_read2_b32 v[166:167], v120 offset0:132 offset1:196
	ds_read2st64_b32 v[168:169], v121 offset1:1
	ds_read2_b32 v[170:171], v121 offset0:132 offset1:196
	ds_read2st64_b32 v[172:173], v122 offset1:1
	ds_read2_b32 v[174:175], v122 offset0:132 offset1:196
	ds_read2st64_b32 v[176:177], v123 offset1:1
	ds_read2_b32 v[178:179], v123 offset0:132 offset1:196
	ds_read2st64_b32 v[180:181], v124 offset1:1
	ds_read2_b32 v[182:183], v124 offset0:132 offset1:196
	v_add_u32_e32 v126, 0x12820, v55
	s_waitcnt lgkmcnt(0)
	v_pk_mul_f32 v[184:185], v[70:71], v[68:69] op_sel:[0,1]
	v_pk_fma_f32 v[186:187], v[66:67], v[68:69], v[184:185] neg_lo:[0,0,1] neg_hi:[0,0,1]
	v_pk_fma_f32 v[188:189], v[66:67], v[68:69], v[184:185] op_sel_hi:[1,0,1]
	v_mov_b32_e32 v187, v189
	v_pk_add_f32 v[192:193], v[186:187], v[152:153]
	v_cvt_pk_bf16_f32 v190, v192, s0
	ds_write_b16 v126, v190
	v_cvt_pk_bf16_f32 v191, v193, s0
	ds_write_b16 v126, v191 offset:128
	v_pk_mul_f32 v[184:185], v[70:71], v[192:193] op_sel:[0,1]
	v_pk_fma_f32 v[186:187], v[66:67], v[192:193], v[184:185] neg_lo:[0,0,1] neg_hi:[0,0,1]
	v_pk_fma_f32 v[188:189], v[66:67], v[192:193], v[184:185] op_sel_hi:[1,0,1]
	v_mov_b32_e32 v187, v189
	v_pk_add_f32 v[68:69], v[186:187], v[154:155]
	v_cvt_pk_bf16_f32 v190, v68, s0
	ds_write_b16 v126, v190 offset:272
	v_cvt_pk_bf16_f32 v191, v69, s0
	ds_write_b16 v126, v191 offset:400
	v_pk_mul_f32 v[184:185], v[70:71], v[68:69] op_sel:[0,1]
	v_pk_fma_f32 v[186:187], v[66:67], v[68:69], v[184:185] neg_lo:[0,0,1] neg_hi:[0,0,1]
	v_pk_fma_f32 v[188:189], v[66:67], v[68:69], v[184:185] op_sel_hi:[1,0,1]
	v_mov_b32_e32 v187, v189
	v_pk_add_f32 v[192:193], v[186:187], v[156:157]
	v_cvt_pk_bf16_f32 v190, v192, s0
	ds_write_b16 v126, v190 offset:544
	v_cvt_pk_bf16_f32 v191, v193, s0
	ds_write_b16 v126, v191 offset:672
	v_pk_mul_f32 v[184:185], v[70:71], v[192:193] op_sel:[0,1]
	v_pk_fma_f32 v[186:187], v[66:67], v[192:193], v[184:185] neg_lo:[0,0,1] neg_hi:[0,0,1]
	v_pk_fma_f32 v[188:189], v[66:67], v[192:193], v[184:185] op_sel_hi:[1,0,1]
	v_mov_b32_e32 v187, v189
	v_pk_add_f32 v[68:69], v[186:187], v[158:159]
	v_cvt_pk_bf16_f32 v190, v68, s0
	ds_write_b16 v126, v190 offset:816
	v_cvt_pk_bf16_f32 v191, v69, s0
	ds_write_b16 v126, v191 offset:944
	v_pk_mul_f32 v[184:185], v[70:71], v[68:69] op_sel:[0,1]
	v_pk_fma_f32 v[186:187], v[66:67], v[68:69], v[184:185] neg_lo:[0,0,1] neg_hi:[0,0,1]
	v_pk_fma_f32 v[188:189], v[66:67], v[68:69], v[184:185] op_sel_hi:[1,0,1]
	v_mov_b32_e32 v187, v189
	v_pk_add_f32 v[192:193], v[186:187], v[160:161]
	v_cvt_pk_bf16_f32 v190, v192, s0
	ds_write_b16 v126, v190 offset:1088
	v_cvt_pk_bf16_f32 v191, v193, s0
	ds_write_b16 v126, v191 offset:1216
	v_pk_mul_f32 v[184:185], v[70:71], v[192:193] op_sel:[0,1]
	v_pk_fma_f32 v[186:187], v[66:67], v[192:193], v[184:185] neg_lo:[0,0,1] neg_hi:[0,0,1]
	v_pk_fma_f32 v[188:189], v[66:67], v[192:193], v[184:185] op_sel_hi:[1,0,1]
	v_mov_b32_e32 v187, v189
	v_pk_add_f32 v[68:69], v[186:187], v[162:163]
	v_cvt_pk_bf16_f32 v190, v68, s0
	ds_write_b16 v126, v190 offset:1360
	v_cvt_pk_bf16_f32 v191, v69, s0
	ds_write_b16 v126, v191 offset:1488
	v_pk_mul_f32 v[184:185], v[70:71], v[68:69] op_sel:[0,1]
	v_pk_fma_f32 v[186:187], v[66:67], v[68:69], v[184:185] neg_lo:[0,0,1] neg_hi:[0,0,1]
	v_pk_fma_f32 v[188:189], v[66:67], v[68:69], v[184:185] op_sel_hi:[1,0,1]
	v_mov_b32_e32 v187, v189
	v_pk_add_f32 v[192:193], v[186:187], v[164:165]
	v_cvt_pk_bf16_f32 v190, v192, s0
	ds_write_b16 v126, v190 offset:1632
	v_cvt_pk_bf16_f32 v191, v193, s0
	ds_write_b16 v126, v191 offset:1760
	v_pk_mul_f32 v[184:185], v[70:71], v[192:193] op_sel:[0,1]
	v_pk_fma_f32 v[186:187], v[66:67], v[192:193], v[184:185] neg_lo:[0,0,1] neg_hi:[0,0,1]
	v_pk_fma_f32 v[188:189], v[66:67], v[192:193], v[184:185] op_sel_hi:[1,0,1]
	v_mov_b32_e32 v187, v189
	v_pk_add_f32 v[68:69], v[186:187], v[166:167]
	v_cvt_pk_bf16_f32 v190, v68, s0
	ds_write_b16 v126, v190 offset:1904
	v_cvt_pk_bf16_f32 v191, v69, s0
	ds_write_b16 v126, v191 offset:2032
	v_pk_mul_f32 v[184:185], v[70:71], v[68:69] op_sel:[0,1]
	v_pk_fma_f32 v[186:187], v[66:67], v[68:69], v[184:185] neg_lo:[0,0,1] neg_hi:[0,0,1]
	v_pk_fma_f32 v[188:189], v[66:67], v[68:69], v[184:185] op_sel_hi:[1,0,1]
	v_mov_b32_e32 v187, v189
	v_pk_add_f32 v[192:193], v[186:187], v[168:169]
	v_cvt_pk_bf16_f32 v190, v192, s0
	ds_write_b16 v126, v190 offset:2176
	v_cvt_pk_bf16_f32 v191, v193, s0
	ds_write_b16 v126, v191 offset:2304
	v_pk_mul_f32 v[184:185], v[70:71], v[192:193] op_sel:[0,1]
	v_pk_fma_f32 v[186:187], v[66:67], v[192:193], v[184:185] neg_lo:[0,0,1] neg_hi:[0,0,1]
	v_pk_fma_f32 v[188:189], v[66:67], v[192:193], v[184:185] op_sel_hi:[1,0,1]
	v_mov_b32_e32 v187, v189
	v_pk_add_f32 v[68:69], v[186:187], v[170:171]
	v_cvt_pk_bf16_f32 v190, v68, s0
	ds_write_b16 v126, v190 offset:2448
	v_cvt_pk_bf16_f32 v191, v69, s0
	ds_write_b16 v126, v191 offset:2576
	v_pk_mul_f32 v[184:185], v[70:71], v[68:69] op_sel:[0,1]
	v_pk_fma_f32 v[186:187], v[66:67], v[68:69], v[184:185] neg_lo:[0,0,1] neg_hi:[0,0,1]
; DI u16 f2bf(float x) { return (u16)(pk2(x, 0.f) & 0xffffu); }
; DI float bf2f(u16 h) { return __uint_as_float(((unsigned)h) << 16); }
; DI f32x4 mfma16(bf16x8 a, bf16x8 b, f32x4 c) { return __builtin_amdgcn_mfma_f32_16x16x32_bf16(a, b, c, 0, 0, 0); }
; template <bool OUT>
; DI void s5_item(int wv0, PP p, int item, unsigned char* smem) {
;     ...
;     for (int t = 0; t < 16; ++t) {
;       const float bur = sBU[t * 132 + lane], bui = sBU[t * 132 + 64 + lane];
;       const float nr = lbr * hr - lbi * hi + bur;
;       const float nim = lbr * hi + lbi * hr + bui;
;       hr = nr;
;       hi = nim;
;       if (OUT) {
;         sH[t * 136 + lane] = f2bf(hr);
;         sH[t * 136 + 64 + lane] = f2bf(hi);
;       }
;     }
;     __syncthreads();
;     if (OUT) {
;       f32x4 y = {0.f, 0.f, 0.f, 0.f};
; #pragma unroll
;       for (int ks = 0; ks < 4; ++ks) y = mfma16(*(const bf16x8*)(sH + fr * 136 + 32 * ks + 8 * fq), cf[ks], y);
; #pragma unroll
;       for (int j = 0; j < 4; ++j) {
;         const size_t o = (size_t)(sub * 16 + 4 * fq + j) * 512 + fr;
;         YS[o] = f2bf(gelu_t(y[j] + dk * bf2f(usk[sub][j])));
;       }
;       __syncthreads();
	v_pk_fma_f32 v[188:189], v[66:67], v[68:69], v[184:185] op_sel_hi:[1,0,1]
	v_mov_b32_e32 v187, v189
	v_pk_add_f32 v[192:193], v[186:187], v[172:173]
	v_cvt_pk_bf16_f32 v190, v192, s0
	ds_write_b16 v126, v190 offset:2720
	v_cvt_pk_bf16_f32 v191, v193, s0
	ds_write_b16 v126, v191 offset:2848
	v_pk_mul_f32 v[184:185], v[70:71], v[192:193] op_sel:[0,1]
	v_pk_fma_f32 v[186:187], v[66:67], v[192:193], v[184:185] neg_lo:[0,0,1] neg_hi:[0,0,1]
	v_pk_fma_f32 v[188:189], v[66:67], v[192:193], v[184:185] op_sel_hi:[1,0,1]
	v_mov_b32_e32 v187, v189
	v_pk_add_f32 v[68:69], v[186:187], v[174:175]
	v_cvt_pk_bf16_f32 v190, v68, s0
	ds_write_b16 v126, v190 offset:2992
	v_cvt_pk_bf16_f32 v191, v69, s0
	ds_write_b16 v126, v191 offset:3120
	v_pk_mul_f32 v[184:185], v[70:71], v[68:69] op_sel:[0,1]
	v_pk_fma_f32 v[186:187], v[66:67], v[68:69], v[184:185] neg_lo:[0,0,1] neg_hi:[0,0,1]
	v_pk_fma_f32 v[188:189], v[66:67], v[68:69], v[184:185] op_sel_hi:[1,0,1]
	v_mov_b32_e32 v187, v189
	v_pk_add_f32 v[192:193], v[186:187], v[176:177]
	v_cvt_pk_bf16_f32 v190, v192, s0
	ds_write_b16 v126, v190 offset:3264
	v_cvt_pk_bf16_f32 v191, v193, s0
	ds_write_b16 v126, v191 offset:3392
	v_pk_mul_f32 v[184:185], v[70:71], v[192:193] op_sel:[0,1]
	v_pk_fma_f32 v[186:187], v[66:67], v[192:193], v[184:185] neg_lo:[0,0,1] neg_hi:[0,0,1]
	v_pk_fma_f32 v[188:189], v[66:67], v[192:193], v[184:185] op_sel_hi:[1,0,1]
	v_mov_b32_e32 v187, v189
	v_pk_add_f32 v[68:69], v[186:187], v[178:179]
	v_cvt_pk_bf16_f32 v190, v68, s0
	ds_write_b16 v126, v190 offset:3536
	v_cvt_pk_bf16_f32 v191, v69, s0
	ds_write_b16 v126, v191 offset:3664
	v_pk_mul_f32 v[184:185], v[70:71], v[68:69] op_sel:[0,1]
	v_pk_fma_f32 v[186:187], v[66:67], v[68:69], v[184:185] neg_lo:[0,0,1] neg_hi:[0,0,1]
	v_pk_fma_f32 v[188:189], v[66:67], v[68:69], v[184:185] op_sel_hi:[1,0,1]
	v_mov_b32_e32 v187, v189
	v_pk_add_f32 v[192:193], v[186:187], v[180:181]
	v_cvt_pk_bf16_f32 v190, v192, s0
	ds_write_b16 v126, v190 offset:3808
	v_cvt_pk_bf16_f32 v191, v193, s0
	ds_write_b16 v126, v191 offset:3936
	v_pk_mul_f32 v[184:185], v[70:71], v[192:193] op_sel:[0,1]
	v_pk_fma_f32 v[186:187], v[66:67], v[192:193], v[184:185] neg_lo:[0,0,1] neg_hi:[0,0,1]
	v_pk_fma_f32 v[188:189], v[66:67], v[192:193], v[184:185] op_sel_hi:[1,0,1]
	v_mov_b32_e32 v187, v189
	v_pk_add_f32 v[68:69], v[186:187], v[182:183]
	v_cvt_pk_bf16_f32 v190, v68, s0
	ds_write_b16 v126, v190 offset:4080
	v_cvt_pk_bf16_f32 v191, v69, s0
	ds_write_b16 v126, v191 offset:4208
	s_waitcnt lgkmcnt(0)
	s_barrier
	ds_read_b128 v[54:57], v0
	ds_read_b128 v[58:61], v0 offset:64
	s_waitcnt vmcnt(12)
	v_mfma_f32_16x16x32_bf16 v[26:29], v[18:21], v[26:29], 0
	s_waitcnt lgkmcnt(1)
	v_mfma_f32_16x16x32_bf16 v[54:57], v[54:57], v[14:17], 0
	s_waitcnt lgkmcnt(0)
	v_mfma_f32_16x16x32_bf16 v[54:57], v[58:61], v[10:13], v[54:57]
	ds_read_b128 v[58:61], v0 offset:128
	v_mfma_f32_16x16x32_bf16 v[22:25], v[18:21], v[22:25], 0
	s_waitcnt lgkmcnt(0)
	v_mfma_f32_16x16x32_bf16 v[54:57], v[58:61], v[6:9], v[54:57]
	ds_read_b128 v[58:61], v0 offset:192
	s_waitcnt lgkmcnt(0)
	v_mfma_f32_16x16x32_bf16 v[54:57], v[58:61], v[2:5], v[54:57]
	v_lshlrev_b32_e32 v58, 16, v90
	s_nop 6
	v_fma_f32 v54, v72, v58, v54
	v_mul_f32_e32 v58, 0x3d372713, v54
	v_mul_f32_e32 v58, v54, v58
	v_fma_f32 v58, v54, v58, v54
	v_mul_f32_e32 v58, 0x3f4c422a, v58
	v_add_f32_e32 v58, v58, v58
	v_mul_f32_e32 v58, 0x3fb8aa3b, v58
	v_exp_f32_e32 v58, v58
	v_mul_f32_e32 v54, 0.5, v54
	v_add_f32_e32 v58, 1.0, v58
	v_div_scale_f32 v59, s[4:5], v58, v58, 2.0
	v_rcp_f32_e32 v60, v59
	s_nop 0
	v_fma_f32 v61, -v59, v60, 1.0
	v_fmac_f32_e32 v60, v61, v60
	v_div_scale_f32 v61, vcc, 2.0, v58, 2.0
	v_mul_f32_e32 v64, v61, v60
	v_fma_f32 v65, -v59, v64, v61
	v_fmac_f32_e32 v64, v65, v60
	v_fma_f32 v59, -v59, v64, v61
	v_div_fmas_f32 v59, v59, v60, v64
	v_div_fixup_f32 v58, v59, v58, 2.0
	v_sub_f32_e32 v58, 1.0, v58
	v_add_f32_e32 v58, 1.0, v58
	v_mul_f32_e32 v54, v54, v58
	v_cvt_pk_bf16_f32 v54, v54, s0
	global_store_short v89, v54, s[2:3]
	v_lshlrev_b32_e32 v54, 16, v88
	v_fma_f32 v54, v72, v54, v55
	v_mul_f32_e32 v55, 0x3d372713, v54
	v_mul_f32_e32 v55, v54, v55
	v_fma_f32 v55, v54, v55, v54
	v_mul_f32_e32 v55, 0x3f4c422a, v55
	v_add_f32_e32 v55, v55, v55
	v_mul_f32_e32 v55, 0x3fb8aa3b, v55
	v_exp_f32_e32 v55, v55
	v_mul_f32_e32 v54, 0.5, v54
	v_add_f32_e32 v55, 1.0, v55
	v_div_scale_f32 v58, s[4:5], v55, v55, 2.0
	v_rcp_f32_e32 v59, v58
	s_nop 0
	v_fma_f32 v60, -v58, v59, 1.0
	v_fmac_f32_e32 v59, v60, v59
	v_div_scale_f32 v60, vcc, 2.0, v55, 2.0
	v_mul_f32_e32 v61, v60, v59
	v_fma_f32 v64, -v58, v61, v60
	v_fmac_f32_e32 v61, v64, v59
	v_fma_f32 v58, -v58, v61, v60
	v_div_fmas_f32 v58, v58, v59, v61
	v_div_fixup_f32 v55, v58, v55, 2.0
	v_sub_f32_e32 v55, 1.0, v55
	v_add_f32_e32 v55, 1.0, v55
	v_mul_f32_e32 v54, v54, v55
	v_cvt_pk_bf16_f32 v54, v54, s0
	global_store_short v87, v54, s[2:3]
	v_lshlrev_b32_e32 v54, 16, v86
	v_fma_f32 v54, v72, v54, v56
	v_mul_f32_e32 v55, 0x3d372713, v54
	v_mul_f32_e32 v55, v54, v55
	v_fma_f32 v55, v54, v55, v54
	v_mul_f32_e32 v55, 0x3f4c422a, v55
	v_add_f32_e32 v55, v55, v55
	v_mul_f32_e32 v55, 0x3fb8aa3b, v55
	v_exp_f32_e32 v55, v55
	v_mul_f32_e32 v54, 0.5, v54
	v_add_f32_e32 v55, 1.0, v55
	v_div_scale_f32 v56, s[4:5], v55, v55, 2.0
	v_rcp_f32_e32 v58, v56
	s_nop 0
	v_fma_f32 v59, -v56, v58, 1.0
	v_fmac_f32_e32 v58, v59, v58
	v_div_scale_f32 v59, vcc, 2.0, v55, 2.0
	v_mul_f32_e32 v60, v59, v58
	v_fma_f32 v61, -v56, v60, v59
	v_fmac_f32_e32 v60, v61, v58
	v_fma_f32 v56, -v56, v60, v59
	v_div_fmas_f32 v56, v56, v58, v60
	v_div_fixup_f32 v55, v56, v55, 2.0
	v_sub_f32_e32 v55, 1.0, v55
	v_add_f32_e32 v55, 1.0, v55
	v_mul_f32_e32 v54, v54, v55
	v_cvt_pk_bf16_f32 v54, v54, s0
	global_store_short v85, v54, s[2:3]
	v_lshlrev_b32_e32 v54, 16, v84
	v_fmac_f32_e32 v57, v72, v54
	v_mul_f32_e32 v54, 0x3d372713, v57
	v_mul_f32_e32 v54, v57, v54
	v_fma_f32 v54, v57, v54, v57
	v_mul_f32_e32 v54, 0x3f4c422a, v54
	v_add_f32_e32 v54, v54, v54
	v_mul_f32_e32 v54, 0x3fb8aa3b, v54
	v_exp_f32_e32 v54, v54
	s_nop 0
	v_add_f32_e32 v54, 1.0, v54
	v_div_scale_f32 v55, s[4:5], v54, v54, 2.0
	v_rcp_f32_e32 v56, v55
	s_mov_b32 s4, 16
	v_fma_f32 v58, -v55, v56, 1.0
	v_fmac_f32_e32 v56, v58, v56
	v_div_scale_f32 v58, vcc, 2.0, v54, 2.0
	v_mul_f32_e32 v59, v58, v56
	v_fma_f32 v60, -v55, v59, v58
	v_fmac_f32_e32 v59, v60, v56
	v_fma_f32 v55, -v55, v59, v58
	v_div_fmas_f32 v55, v55, v56, v59
	v_div_fixup_f32 v54, v55, v54, 2.0
	v_sub_f32_e32 v54, 1.0, v54
	v_mul_f32_e32 v55, 0.5, v57
	v_add_f32_e32 v54, 1.0, v54
	v_mul_f32_e32 v54, v55, v54
	v_cvt_pk_bf16_f32 v54, v54, s0
	global_store_short v83, v54, s[2:3]
	s_barrier
; DI u16 f2bf(float x) { return (u16)(pk2(x, 0.f) & 0xffffu); }
; DI f32x4 mfma16(bf16x8 a, bf16x8 b, f32x4 c) { return __builtin_amdgcn_mfma_f32_16x16x32_bf16(a, b, c, 0, 0, 0); }
; template <bool OUT>
; DI void s5_item(int wv0, PP p, int item, unsigned char* smem) {
;     ...
;     for (int nt = 0; nt < 8; ++nt) {
;       const f32x4 a = mfma16(ua, bb[nt], f32x4{0.f, 0.f, 0.f, 0.f});
; #pragma unroll
;       for (int j = 0; j < 4; ++j) sBU[(4 * fq + j) * 132 + 16 * nt + fr] = a[j];
;     }
;     __syncthreads();
; #pragma unroll 4
;     for (int t = 0; t < 16; ++t) {
;       const float bur = sBU[t * 132 + lane], bui = sBU[t * 132 + 64 + lane];
;       const float nr = lbr * hr - lbi * hi + bur;
;       const float nim = lbr * hi + lbi * hr + bui;
;       hr = nr;
;       hi = nim;
;       if (OUT) {
;         sH[t * 136 + lane] = f2bf(hr);
;         sH[t * 136 + 64 + lane] = f2bf(hi);
;       }
;     }
	ds_write_b32 v63, v26 offset:8192
	ds_write_b32 v62, v27 offset:8192
	ds_write_b32 v62, v28 offset:8720
	ds_write_b32 v62, v29 offset:9248
	ds_write_b32 v63, v22 offset:8256
	ds_write_b32 v62, v23 offset:8256
	ds_write_b32 v62, v24 offset:8784
	ds_write_b32 v62, v25 offset:9312
	v_mfma_f32_16x16x32_bf16 v[22:25], v[18:21], v[34:37], 0
	s_nop 7
	ds_write_b32 v63, v22 offset:8320
	ds_write_b32 v62, v23 offset:8320
	ds_write_b32 v62, v24 offset:8848
	ds_write_b32 v62, v25 offset:9376
	v_mfma_f32_16x16x32_bf16 v[22:25], v[18:21], v[30:33], 0
	s_nop 7
	ds_write_b32 v63, v22 offset:8384
	ds_write_b32 v62, v23 offset:8384
	ds_write_b32 v62, v24 offset:8912
	ds_write_b32 v62, v25 offset:9440
	v_mfma_f32_16x16x32_bf16 v[22:25], v[18:21], v[42:45], 0
	s_nop 7
	ds_write_b32 v63, v22 offset:8448
	ds_write_b32 v62, v23 offset:8448
	ds_write_b32 v62, v24 offset:8976
	ds_write_b32 v62, v25 offset:9504
	v_mfma_f32_16x16x32_bf16 v[22:25], v[18:21], v[38:41], 0
	s_nop 7
	ds_write_b32 v63, v22 offset:8512
	ds_write_b32 v62, v23 offset:8512
	ds_write_b32 v62, v24 offset:9040
	ds_write_b32 v62, v25 offset:9568
	v_mfma_f32_16x16x32_bf16 v[22:25], v[18:21], v[50:53], 0
	s_nop 7
	ds_write_b32 v63, v22 offset:8576
	ds_write_b32 v62, v23 offset:8576
	ds_write_b32 v62, v24 offset:9104
	ds_write_b32 v62, v25 offset:9632
	v_mfma_f32_16x16x32_bf16 v[18:21], v[18:21], v[46:49], 0
	s_nop 7
	ds_write_b32 v63, v18 offset:8640
	ds_write_b32 v62, v19 offset:8640
	ds_write_b32 v62, v20 offset:9168
	ds_write_b32 v62, v21 offset:9696
	s_waitcnt lgkmcnt(0)
	s_barrier
.LBB0_790:
	v_add_u32_e32 v117, 32, v82
	v_add_u32_e32 v118, 1088, v82
	v_add_u32_e32 v119, 2144, v82
	v_add_u32_e32 v120, 3200, v82
	v_add_u32_e32 v121, 4256, v82
	v_add_u32_e32 v122, 5312, v82
	v_add_u32_e32 v123, 6368, v82
	v_add_u32_e32 v124, 7424, v82
	ds_read2st64_b32 v[152:153], v117 offset1:1
	ds_read2_b32 v[154:155], v117 offset0:132 offset1:196
	ds_read2st64_b32 v[156:157], v118 offset1:1
	ds_read2_b32 v[158:159], v118 offset0:132 offset1:196
	ds_read2st64_b32 v[160:161], v119 offset1:1
	ds_read2_b32 v[162:163], v119 offset0:132 offset1:196
	ds_read2st64_b32 v[164:165], v120 offset1:1
	ds_read2_b32 v[166:167], v120 offset0:132 offset1:196
	ds_read2st64_b32 v[168:169], v121 offset1:1
	ds_read2_b32 v[170:171], v121 offset0:132 offset1:196
	ds_read2st64_b32 v[172:173], v122 offset1:1
	ds_read2_b32 v[174:175], v122 offset0:132 offset1:196
	ds_read2st64_b32 v[176:177], v123 offset1:1
	ds_read2_b32 v[178:179], v123 offset0:132 offset1:196
	ds_read2st64_b32 v[180:181], v124 offset1:1
	ds_read2_b32 v[182:183], v124 offset0:132 offset1:196
	v_add_u32_e32 v126, 0x12820, v81
	s_waitcnt lgkmcnt(0)
	v_pk_mul_f32 v[184:185], v[70:71], v[68:69] op_sel:[0,1]
	v_pk_fma_f32 v[186:187], v[66:67], v[68:69], v[184:185] neg_lo:[0,0,1] neg_hi:[0,0,1]
	v_pk_fma_f32 v[188:189], v[66:67], v[68:69], v[184:185] op_sel_hi:[1,0,1]
	v_mov_b32_e32 v187, v189
	v_pk_add_f32 v[192:193], v[186:187], v[152:153]
	v_cvt_pk_bf16_f32 v190, v192, s0
	ds_write_b16 v126, v190
	v_cvt_pk_bf16_f32 v191, v193, s0
	ds_write_b16 v126, v191 offset:128
	v_pk_mul_f32 v[184:185], v[70:71], v[192:193] op_sel:[0,1]
	v_pk_fma_f32 v[186:187], v[66:67], v[192:193], v[184:185] neg_lo:[0,0,1] neg_hi:[0,0,1]
	v_pk_fma_f32 v[188:189], v[66:67], v[192:193], v[184:185] op_sel_hi:[1,0,1]
	v_mov_b32_e32 v187, v189
	v_pk_add_f32 v[68:69], v[186:187], v[154:155]
	v_cvt_pk_bf16_f32 v190, v68, s0
	ds_write_b16 v126, v190 offset:272
	v_cvt_pk_bf16_f32 v191, v69, s0
	ds_write_b16 v126, v191 offset:400
	v_pk_mul_f32 v[184:185], v[70:71], v[68:69] op_sel:[0,1]
	v_pk_fma_f32 v[186:187], v[66:67], v[68:69], v[184:185] neg_lo:[0,0,1] neg_hi:[0,0,1]
	v_pk_fma_f32 v[188:189], v[66:67], v[68:69], v[184:185] op_sel_hi:[1,0,1]
	v_mov_b32_e32 v187, v189
	v_pk_add_f32 v[192:193], v[186:187], v[156:157]
	v_cvt_pk_bf16_f32 v190, v192, s0
	ds_write_b16 v126, v190 offset:544
	v_cvt_pk_bf16_f32 v191, v193, s0
	ds_write_b16 v126, v191 offset:672
	v_pk_mul_f32 v[184:185], v[70:71], v[192:193] op_sel:[0,1]
	v_pk_fma_f32 v[186:187], v[66:67], v[192:193], v[184:185] neg_lo:[0,0,1] neg_hi:[0,0,1]
	v_pk_fma_f32 v[188:189], v[66:67], v[192:193], v[184:185] op_sel_hi:[1,0,1]
	v_mov_b32_e32 v187, v189
	v_pk_add_f32 v[68:69], v[186:187], v[158:159]
	v_cvt_pk_bf16_f32 v190, v68, s0
	ds_write_b16 v126, v190 offset:816
	v_cvt_pk_bf16_f32 v191, v69, s0
	ds_write_b16 v126, v191 offset:944
	v_pk_mul_f32 v[184:185], v[70:71], v[68:69] op_sel:[0,1]
	v_pk_fma_f32 v[186:187], v[66:67], v[68:69], v[184:185] neg_lo:[0,0,1] neg_hi:[0,0,1]
	v_pk_fma_f32 v[188:189], v[66:67], v[68:69], v[184:185] op_sel_hi:[1,0,1]
	v_mov_b32_e32 v187, v189
	v_pk_add_f32 v[192:193], v[186:187], v[160:161]
	v_cvt_pk_bf16_f32 v190, v192, s0
	ds_write_b16 v126, v190 offset:1088
	v_cvt_pk_bf16_f32 v191, v193, s0
	ds_write_b16 v126, v191 offset:1216
	v_pk_mul_f32 v[184:185], v[70:71], v[192:193] op_sel:[0,1]
	v_pk_fma_f32 v[186:187], v[66:67], v[192:193], v[184:185] neg_lo:[0,0,1] neg_hi:[0,0,1]
	v_pk_fma_f32 v[188:189], v[66:67], v[192:193], v[184:185] op_sel_hi:[1,0,1]
	v_mov_b32_e32 v187, v189
	v_pk_add_f32 v[68:69], v[186:187], v[162:163]
	v_cvt_pk_bf16_f32 v190, v68, s0
	ds_write_b16 v126, v190 offset:1360
	v_cvt_pk_bf16_f32 v191, v69, s0
	ds_write_b16 v126, v191 offset:1488
	v_pk_mul_f32 v[184:185], v[70:71], v[68:69] op_sel:[0,1]
	v_pk_fma_f32 v[186:187], v[66:67], v[68:69], v[184:185] neg_lo:[0,0,1] neg_hi:[0,0,1]
	v_pk_fma_f32 v[188:189], v[66:67], v[68:69], v[184:185] op_sel_hi:[1,0,1]
	v_mov_b32_e32 v187, v189
	v_pk_add_f32 v[192:193], v[186:187], v[164:165]
	v_cvt_pk_bf16_f32 v190, v192, s0
	ds_write_b16 v126, v190 offset:1632
; DI u16 f2bf(float x) { return (u16)(pk2(x, 0.f) & 0xffffu); }
; template <bool OUT>
; DI void s5_item(int wv0, PP p, int item, unsigned char* smem) {
;     ...
;     for (int t = 0; t < 16; ++t) {
;       const float bur = sBU[t * 132 + lane], bui = sBU[t * 132 + 64 + lane];
;       const float nr = lbr * hr - lbi * hi + bur;
;       const float nim = lbr * hi + lbi * hr + bui;
;       hr = nr;
;       hi = nim;
;       if (OUT) {
;         sH[t * 136 + lane] = f2bf(hr);
;         sH[t * 136 + 64 + lane] = f2bf(hi);
;       }
;     }
;     __syncthreads();
	v_cvt_pk_bf16_f32 v191, v193, s0
	ds_write_b16 v126, v191 offset:1760
	v_pk_mul_f32 v[184:185], v[70:71], v[192:193] op_sel:[0,1]
	v_pk_fma_f32 v[186:187], v[66:67], v[192:193], v[184:185] neg_lo:[0,0,1] neg_hi:[0,0,1]
	v_pk_fma_f32 v[188:189], v[66:67], v[192:193], v[184:185] op_sel_hi:[1,0,1]
	v_mov_b32_e32 v187, v189
	v_pk_add_f32 v[68:69], v[186:187], v[166:167]
	v_cvt_pk_bf16_f32 v190, v68, s0
	ds_write_b16 v126, v190 offset:1904
	v_cvt_pk_bf16_f32 v191, v69, s0
	ds_write_b16 v126, v191 offset:2032
	v_pk_mul_f32 v[184:185], v[70:71], v[68:69] op_sel:[0,1]
	v_pk_fma_f32 v[186:187], v[66:67], v[68:69], v[184:185] neg_lo:[0,0,1] neg_hi:[0,0,1]
	v_pk_fma_f32 v[188:189], v[66:67], v[68:69], v[184:185] op_sel_hi:[1,0,1]
	v_mov_b32_e32 v187, v189
	v_pk_add_f32 v[192:193], v[186:187], v[168:169]
	v_cvt_pk_bf16_f32 v190, v192, s0
	ds_write_b16 v126, v190 offset:2176
	v_cvt_pk_bf16_f32 v191, v193, s0
	ds_write_b16 v126, v191 offset:2304
	v_pk_mul_f32 v[184:185], v[70:71], v[192:193] op_sel:[0,1]
	v_pk_fma_f32 v[186:187], v[66:67], v[192:193], v[184:185] neg_lo:[0,0,1] neg_hi:[0,0,1]
	v_pk_fma_f32 v[188:189], v[66:67], v[192:193], v[184:185] op_sel_hi:[1,0,1]
	v_mov_b32_e32 v187, v189
	v_pk_add_f32 v[68:69], v[186:187], v[170:171]
	v_cvt_pk_bf16_f32 v190, v68, s0
	ds_write_b16 v126, v190 offset:2448
	v_cvt_pk_bf16_f32 v191, v69, s0
	ds_write_b16 v126, v191 offset:2576
	v_pk_mul_f32 v[184:185], v[70:71], v[68:69] op_sel:[0,1]
	v_pk_fma_f32 v[186:187], v[66:67], v[68:69], v[184:185] neg_lo:[0,0,1] neg_hi:[0,0,1]
	v_pk_fma_f32 v[188:189], v[66:67], v[68:69], v[184:185] op_sel_hi:[1,0,1]
	v_mov_b32_e32 v187, v189
	v_pk_add_f32 v[192:193], v[186:187], v[172:173]
	v_cvt_pk_bf16_f32 v190, v192, s0
	ds_write_b16 v126, v190 offset:2720
	v_cvt_pk_bf16_f32 v191, v193, s0
	ds_write_b16 v126, v191 offset:2848
	v_pk_mul_f32 v[184:185], v[70:71], v[192:193] op_sel:[0,1]
	v_pk_fma_f32 v[186:187], v[66:67], v[192:193], v[184:185] neg_lo:[0,0,1] neg_hi:[0,0,1]
	v_pk_fma_f32 v[188:189], v[66:67], v[192:193], v[184:185] op_sel_hi:[1,0,1]
	v_mov_b32_e32 v187, v189
	v_pk_add_f32 v[68:69], v[186:187], v[174:175]
	v_cvt_pk_bf16_f32 v190, v68, s0
	ds_write_b16 v126, v190 offset:2992
	v_cvt_pk_bf16_f32 v191, v69, s0
	ds_write_b16 v126, v191 offset:3120
	v_pk_mul_f32 v[184:185], v[70:71], v[68:69] op_sel:[0,1]
	v_pk_fma_f32 v[186:187], v[66:67], v[68:69], v[184:185] neg_lo:[0,0,1] neg_hi:[0,0,1]
	v_pk_fma_f32 v[188:189], v[66:67], v[68:69], v[184:185] op_sel_hi:[1,0,1]
	v_mov_b32_e32 v187, v189
	v_pk_add_f32 v[192:193], v[186:187], v[176:177]
	v_cvt_pk_bf16_f32 v190, v192, s0
	ds_write_b16 v126, v190 offset:3264
	v_cvt_pk_bf16_f32 v191, v193, s0
	ds_write_b16 v126, v191 offset:3392
	v_pk_mul_f32 v[184:185], v[70:71], v[192:193] op_sel:[0,1]
	v_pk_fma_f32 v[186:187], v[66:67], v[192:193], v[184:185] neg_lo:[0,0,1] neg_hi:[0,0,1]
	v_pk_fma_f32 v[188:189], v[66:67], v[192:193], v[184:185] op_sel_hi:[1,0,1]
	v_mov_b32_e32 v187, v189
	v_pk_add_f32 v[68:69], v[186:187], v[178:179]
	v_cvt_pk_bf16_f32 v190, v68, s0
	ds_write_b16 v126, v190 offset:3536
	v_cvt_pk_bf16_f32 v191, v69, s0
	ds_write_b16 v126, v191 offset:3664
	v_pk_mul_f32 v[184:185], v[70:71], v[68:69] op_sel:[0,1]
	v_pk_fma_f32 v[186:187], v[66:67], v[68:69], v[184:185] neg_lo:[0,0,1] neg_hi:[0,0,1]
	v_pk_fma_f32 v[188:189], v[66:67], v[68:69], v[184:185] op_sel_hi:[1,0,1]
	v_mov_b32_e32 v187, v189
	v_pk_add_f32 v[192:193], v[186:187], v[180:181]
	v_cvt_pk_bf16_f32 v190, v192, s0
	ds_write_b16 v126, v190 offset:3808
	v_cvt_pk_bf16_f32 v191, v193, s0
	ds_write_b16 v126, v191 offset:3936
	v_pk_mul_f32 v[184:185], v[70:71], v[192:193] op_sel:[0,1]
	v_pk_fma_f32 v[186:187], v[66:67], v[192:193], v[184:185] neg_lo:[0,0,1] neg_hi:[0,0,1]
	v_pk_fma_f32 v[188:189], v[66:67], v[192:193], v[184:185] op_sel_hi:[1,0,1]
	v_mov_b32_e32 v187, v189
	v_pk_add_f32 v[68:69], v[186:187], v[182:183]
	v_cvt_pk_bf16_f32 v190, v68, s0
	ds_write_b16 v126, v190 offset:4080
	v_cvt_pk_bf16_f32 v191, v69, s0
	ds_write_b16 v126, v191 offset:4208
	s_waitcnt lgkmcnt(0)
	s_barrier
; DI u16 f2bf(float x) { return (u16)(pk2(x, 0.f) & 0xffffu); }
; DI float bf2f(u16 h) { return __uint_as_float(((unsigned)h) << 16); }
; DI f32x4 mfma16(bf16x8 a, bf16x8 b, f32x4 c) { return __builtin_amdgcn_mfma_f32_16x16x32_bf16(a, b, c, 0, 0, 0); }
; template <bool OUT>
; DI void s5_item(int wv0, PP p, int item, unsigned char* smem) {
;     ...
;     if (OUT) {
;       f32x4 y = {0.f, 0.f, 0.f, 0.f};
; #pragma unroll
;       for (int ks = 0; ks < 4; ++ks) y = mfma16(*(const bf16x8*)(sH + fr * 136 + 32 * ks + 8 * fq), cf[ks], y);
; #pragma unroll
;       for (int j = 0; j < 4; ++j) {
;         const size_t o = (size_t)(sub * 16 + 4 * fq + j) * 512 + fr;
;         YS[o] = f2bf(gelu_t(y[j] + dk * bf2f(usk[sub][j])));
;       }
;       __syncthreads();
;     }
;   }
;   if (!OUT) *HL = make_float2(hr, hi);
;   __syncthreads();
	ds_read_b128 v[18:21], v0
	s_waitcnt lgkmcnt(0)
	v_mfma_f32_16x16x32_bf16 v[14:17], v[18:21], v[14:17], 0
	ds_read_b128 v[18:21], v0 offset:64
	s_waitcnt lgkmcnt(0)
	v_mfma_f32_16x16x32_bf16 v[10:13], v[18:21], v[10:13], v[14:17]
	s_nop 4
	ds_read_b128 v[14:17], v0 offset:128
	s_waitcnt lgkmcnt(0)
	v_mfma_f32_16x16x32_bf16 v[6:9], v[14:17], v[6:9], v[10:13]
	s_nop 2
	ds_read_b128 v[10:13], v0 offset:192
	s_waitcnt vmcnt(15)
	v_lshlrev_b32_e32 v0, 16, v80
	s_waitcnt lgkmcnt(0)
	v_mfma_f32_16x16x32_bf16 v[2:5], v[10:13], v[2:5], v[6:9]
	s_nop 7
	v_fma_f32 v0, v72, v0, v2
	v_mul_f32_e32 v2, 0x3d372713, v0
	v_mul_f32_e32 v2, v0, v2
	v_fma_f32 v2, v0, v2, v0
	v_mul_f32_e32 v2, 0x3f4c422a, v2
	v_add_f32_e32 v2, v2, v2
	v_mul_f32_e32 v2, 0x3fb8aa3b, v2
	v_exp_f32_e32 v2, v2
	v_mul_f32_e32 v0, 0.5, v0
	v_add_f32_e32 v2, 1.0, v2
	v_div_scale_f32 v6, s[4:5], v2, v2, 2.0
	v_rcp_f32_e32 v7, v6
	s_nop 0
	v_fma_f32 v8, -v6, v7, 1.0
	v_fmac_f32_e32 v7, v8, v7
	v_div_scale_f32 v8, vcc, 2.0, v2, 2.0
	v_mul_f32_e32 v9, v8, v7
	v_fma_f32 v10, -v6, v9, v8
	v_fmac_f32_e32 v9, v10, v7
	v_fma_f32 v6, -v6, v9, v8
	v_div_fmas_f32 v6, v6, v7, v9
	v_div_fixup_f32 v2, v6, v2, 2.0
	v_sub_f32_e32 v2, 1.0, v2
	v_add_f32_e32 v2, 1.0, v2
	v_mul_f32_e32 v0, v0, v2
	v_cvt_pk_bf16_f32 v0, v0, s0
	global_store_short v79, v0, s[2:3]
	s_waitcnt vmcnt(15)
	v_lshlrev_b32_e32 v0, 16, v78
	v_fma_f32 v0, v72, v0, v3
	v_mul_f32_e32 v2, 0x3d372713, v0
	v_mul_f32_e32 v2, v0, v2
	v_fma_f32 v2, v0, v2, v0
	v_mul_f32_e32 v2, 0x3f4c422a, v2
	v_add_f32_e32 v2, v2, v2
	v_mul_f32_e32 v2, 0x3fb8aa3b, v2
	v_exp_f32_e32 v2, v2
	v_mul_f32_e32 v0, 0.5, v0
	v_add_f32_e32 v2, 1.0, v2
	v_div_scale_f32 v3, s[4:5], v2, v2, 2.0
	v_rcp_f32_e32 v6, v3
	s_nop 0
	v_fma_f32 v7, -v3, v6, 1.0
	v_fmac_f32_e32 v6, v7, v6
	v_div_scale_f32 v7, vcc, 2.0, v2, 2.0
	v_mul_f32_e32 v8, v7, v6
	v_fma_f32 v9, -v3, v8, v7
	v_fmac_f32_e32 v8, v9, v6
	v_fma_f32 v3, -v3, v8, v7
	v_div_fmas_f32 v3, v3, v6, v8
	v_div_fixup_f32 v2, v3, v2, 2.0
	v_sub_f32_e32 v2, 1.0, v2
	v_add_f32_e32 v2, 1.0, v2
	v_mul_f32_e32 v0, v0, v2
	v_cvt_pk_bf16_f32 v0, v0, s0
	global_store_short v77, v0, s[2:3]
	s_waitcnt vmcnt(15)
	v_lshlrev_b32_e32 v0, 16, v76
	v_fma_f32 v0, v72, v0, v4
	v_mul_f32_e32 v2, 0x3d372713, v0
	v_mul_f32_e32 v2, v0, v2
	v_fma_f32 v2, v0, v2, v0
	v_mul_f32_e32 v2, 0x3f4c422a, v2
	v_add_f32_e32 v2, v2, v2
	v_mul_f32_e32 v2, 0x3fb8aa3b, v2
	v_exp_f32_e32 v2, v2
	v_mul_f32_e32 v0, 0.5, v0
	v_add_f32_e32 v2, 1.0, v2
	v_div_scale_f32 v3, s[4:5], v2, v2, 2.0
	v_rcp_f32_e32 v4, v3
	s_nop 0
	v_fma_f32 v6, -v3, v4, 1.0
	v_fmac_f32_e32 v4, v6, v4
	v_div_scale_f32 v6, vcc, 2.0, v2, 2.0
	v_mul_f32_e32 v7, v6, v4
	v_fma_f32 v8, -v3, v7, v6
	v_fmac_f32_e32 v7, v8, v4
	v_fma_f32 v3, -v3, v7, v6
	v_div_fmas_f32 v3, v3, v4, v7
	v_div_fixup_f32 v2, v3, v2, 2.0
	v_sub_f32_e32 v2, 1.0, v2
	v_add_f32_e32 v2, 1.0, v2
	v_mul_f32_e32 v0, v0, v2
	v_cvt_pk_bf16_f32 v0, v0, s0
	global_store_short v75, v0, s[2:3]
	s_waitcnt vmcnt(15)
	v_lshlrev_b32_e32 v0, 16, v74
	v_fmac_f32_e32 v5, v72, v0
	v_mul_f32_e32 v0, 0x3d372713, v5
	v_mul_f32_e32 v0, v5, v0
	v_fma_f32 v0, v5, v0, v5
	v_mul_f32_e32 v0, 0x3f4c422a, v0
	v_add_f32_e32 v0, v0, v0
	v_mul_f32_e32 v0, 0x3fb8aa3b, v0
	v_exp_f32_e32 v0, v0
	s_nop 0
	v_add_f32_e32 v0, 1.0, v0
	v_div_scale_f32 v2, s[4:5], v0, v0, 2.0
	v_rcp_f32_e32 v3, v2
	s_nop 0
	v_fma_f32 v4, -v2, v3, 1.0
	v_fmac_f32_e32 v3, v4, v3
	v_div_scale_f32 v4, vcc, 2.0, v0, 2.0
	v_mul_f32_e32 v6, v4, v3
	v_fma_f32 v7, -v2, v6, v4
	v_fmac_f32_e32 v6, v7, v3
	v_fma_f32 v2, -v2, v6, v4
	v_div_fmas_f32 v2, v2, v3, v6
	v_div_fixup_f32 v0, v2, v0, 2.0
	v_sub_f32_e32 v0, 1.0, v0
	v_mul_f32_e32 v2, 0.5, v5
	v_add_f32_e32 v0, 1.0, v0
	v_mul_f32_e32 v0, v2, v0
	v_cvt_pk_bf16_f32 v0, v0, s0
	global_store_short v73, v0, s[2:3]
	s_barrier
	s_barrier
	s_mov_b64 s[2:3], 0
